# sample-row U half also hand-written: coalesced whole-row slices, f32 VALU products on the fp8-decoded values (was fp8 MFMA with a lane-divergent load pattern)
# speedup vs baseline: 1.0081x; 1.0081x over previous
;     DEVI int* eidx() const { return (int*)(ws + WS_EIDX); }
;     ...
;     int e[NTL]; float g[NTL], s_u[NTL], s_v[NTL];
; #pragma unroll
;     for (int t = 0; t < NTL; ++t) { e[t] = eidx[(size_t)r * 128 + (tbase + t) * 16 + n16]; g[t] = gwv[(size_t)r * 128 + (tbase + t) * 16 + n16]; }
; #pragma unroll
;     for (int t = 0; t < NTL; ++t) { s_u[t] = su[e[t]]; s_v[t] = sv[e[t]]; }
;     const unsigned char* up[NTL];
; #pragma unroll
;     for (int t = 0; t < NTL; ++t) up[t] = u8 + (size_t)e[t] * D + kq * 16;
;     const unsigned char* hp = h8 + (n16 < 8 ? (size_t)0 : (size_t)M * D) + (size_t)r * D + kq * 16;
;     f32x4_t acc[NTL];
; #pragma unroll
;     for (int t = 0; t < NTL; ++t) acc[t] = (f32x4_t){0.f, 0.f, 0.f, 0.f};
;     u32x4_t b0[NTL], b1[NTL];
; #pragma unroll
;     for (int t = 0; t < NTL; ++t) { b0[t] = *(const u32x4_t*)(up[t]); b1[t] = *(const u32x4_t*)(up[t] + 64); }
;     ...
;     for (int m = 0; m < 16; m += 2) {
;         const u32x4_t a0 = *(const u32x4_t*)(hp + m * 64), a1 = *(const u32x4_t*)(hp + m * 64 + 64);
; #pragma unroll
;         for (int t = 0; t < NTL; ++t) FP8MM(a0, b0[t], acc[t]);
;         if (m + 2 < 16) {
; #pragma unroll
;             for (int t = 0; t < NTL; ++t) b0[t] = *(const u32x4_t*)(up[t] + (m + 2) * 64);
;         }
; #pragma unroll
;         for (int t = 0; t < NTL; ++t) FP8MM(a1, b1[t], acc[t]);
;         if (m + 3 < 16) {
; #pragma unroll
;             for (int t = 0; t < NTL; ++t) b1[t] = *(const u32x4_t*)(up[t] + (m + 3) * 64);
;         }
;     }
.LBB0_1129:
	s_lshl_b32 s40, s36, 2
	s_add_i32 s24, s40, s62
	s_ashr_i32 s25, s24, 31
	s_lshl_b64 s[28:29], s[24:25], 10
	v_readlane_b32 s26, v253, 41
	v_and_b32_e32 v2, 7, v210
	v_lshrrev_b32_e32 v3, 3, v210
	v_lshlrev_b32_e32 v4, 4, v2
	v_lshlrev_b32_e32 v5, 5, v3
	v_lshlrev_b32_e32 v6, 2, v210
	v_add_u32_e32 v7, 0x880000, v6
	v_add_u32_e32 v8, 0x1100000, v4
	s_lshl_b32 s27, s26, 24
	s_add_u32 s42, s74, 0x1fa42100
	s_addc_u32 s43, s75, 0
	s_add_u32 s42, s42, s27
	s_addc_u32 s43, s43, 0
	s_lshl_b32 s27, s24, 10
	s_add_u32 s44, s74, 0x2fac2100
	s_addc_u32 s45, s75, 0
	s_add_u32 s44, s44, s27
	s_addc_u32 s45, s45, 0
	s_lshl_b32 s27, s24, 9
	s_lshl_b32 s30, s60, 2
	s_add_u32 s64, s74, 0x1b292100
	s_addc_u32 s65, s75, 0
	s_add_u32 s64, s64, s27
	s_addc_u32 s65, s65, 0
	s_add_u32 s64, s64, s30
	s_addc_u32 s65, s65, 0
	s_lshl_b32 s27, s26, 16
	s_add_u32 s66, s74, 0x2fa42100
	s_addc_u32 s67, s75, 0
	s_add_u32 s66, s66, s27
	s_addc_u32 s67, s67, 0
	global_load_dwordx4 v[68:71], v5, s[64:65]
	global_load_dwordx4 v[72:75], v5, s[64:65] offset:16
	global_load_dword v84, v6, s[64:65]
	global_load_dword v85, v7, s[64:65]
	global_load_dwordx4 v[88:91], v4, s[44:45] offset:0
	global_load_dwordx4 v[92:95], v8, s[44:45] offset:0
	global_load_dwordx4 v[96:99], v4, s[44:45] offset:128
	global_load_dwordx4 v[104:107], v8, s[44:45] offset:128
	s_waitcnt vmcnt(6)
	v_lshl_add_u32 v76, v68, 10, v4
	v_lshl_add_u32 v77, v69, 10, v4
	v_lshl_add_u32 v78, v70, 10, v4
	v_lshl_add_u32 v79, v71, 10, v4
	v_lshl_add_u32 v80, v72, 10, v4
	v_lshl_add_u32 v81, v73, 10, v4
	v_lshl_add_u32 v82, v74, 10, v4
	v_lshl_add_u32 v83, v75, 10, v4
	global_load_dwordx4 v[130:133], v76, s[42:43] offset:0
	global_load_dwordx4 v[134:137], v77, s[42:43] offset:0
	global_load_dwordx4 v[138:141], v78, s[42:43] offset:0
	global_load_dwordx4 v[142:145], v79, s[42:43] offset:0
	global_load_dwordx4 v[146:149], v80, s[42:43] offset:0
	global_load_dwordx4 v[150:153], v81, s[42:43] offset:0
	global_load_dwordx4 v[154:157], v82, s[42:43] offset:0
	global_load_dwordx4 v[158:161], v83, s[42:43] offset:0
	global_load_dwordx4 v[162:165], v76, s[42:43] offset:128
	global_load_dwordx4 v[166:169], v77, s[42:43] offset:128
	global_load_dwordx4 v[170:173], v78, s[42:43] offset:128
	global_load_dwordx4 v[180:183], v79, s[42:43] offset:128
	global_load_dwordx4 v[184:187], v80, s[42:43] offset:128
	global_load_dwordx4 v[188:191], v81, s[42:43] offset:128
	global_load_dwordx4 v[192:195], v82, s[42:43] offset:128
	global_load_dwordx4 v[196:199], v83, s[42:43] offset:128
	s_waitcnt vmcnt(21)
	v_lshlrev_b32_e32 v9, 2, v84
	v_add_u32_e32 v42, 0x40000, v9
	global_load_dword v86, v9, s[66:67]
	global_load_dword v87, v42, s[66:67]
	v_mov_b32_e32 v44, 0x3d000000
	v_mov_b32_e32 v45, 0x3d000000
	s_waitcnt vmcnt(20)
	v_cvt_pk_f32_fp8_e32 v[108:109], v88
	v_cvt_pk_f32_fp8_sdwa v[110:111], v88 src0_sel:WORD_1
	v_cvt_pk_f32_fp8_e32 v[112:113], v89
	v_cvt_pk_f32_fp8_sdwa v[114:115], v89 src0_sel:WORD_1
	v_cvt_pk_f32_fp8_e32 v[216:217], v90
	v_cvt_pk_f32_fp8_sdwa v[218:219], v90 src0_sel:WORD_1
	v_cvt_pk_f32_fp8_e32 v[220:221], v91
	v_cvt_pk_f32_fp8_sdwa v[222:223], v91 src0_sel:WORD_1
	v_cvt_pk_f32_fp8_e32 v[48:49], v92
	v_cvt_pk_f32_fp8_sdwa v[50:51], v92 src0_sel:WORD_1
	v_cvt_pk_f32_fp8_e32 v[52:53], v93
	v_cvt_pk_f32_fp8_sdwa v[54:55], v93 src0_sel:WORD_1
	v_cvt_pk_f32_fp8_e32 v[56:57], v94
	v_cvt_pk_f32_fp8_sdwa v[58:59], v94 src0_sel:WORD_1
	v_cvt_pk_f32_fp8_e32 v[60:61], v95
	v_cvt_pk_f32_fp8_sdwa v[62:63], v95 src0_sel:WORD_1
	v_pk_fma_f32 v[108:109], v[48:49], v[44:45], v[108:109]
	v_pk_fma_f32 v[110:111], v[50:51], v[44:45], v[110:111]
	v_pk_fma_f32 v[112:113], v[52:53], v[44:45], v[112:113]
	v_pk_fma_f32 v[114:115], v[54:55], v[44:45], v[114:115]
	v_pk_fma_f32 v[216:217], v[56:57], v[44:45], v[216:217]
	v_pk_fma_f32 v[218:219], v[58:59], v[44:45], v[218:219]
	v_pk_fma_f32 v[220:221], v[60:61], v[44:45], v[220:221]
	v_pk_fma_f32 v[222:223], v[62:63], v[44:45], v[222:223]
	global_load_dwordx4 v[88:91], v4, s[44:45] offset:256
	global_load_dwordx4 v[92:95], v8, s[44:45] offset:256
	s_waitcnt vmcnt(19)
	v_cvt_pk_f32_fp8_e32 v[48:49], v130
	v_cvt_pk_f32_fp8_sdwa v[50:51], v130 src0_sel:WORD_1
	v_cvt_pk_f32_fp8_e32 v[52:53], v131
	v_cvt_pk_f32_fp8_sdwa v[54:55], v131 src0_sel:WORD_1
	v_cvt_pk_f32_fp8_e32 v[56:57], v132
	v_cvt_pk_f32_fp8_sdwa v[58:59], v132 src0_sel:WORD_1
	v_cvt_pk_f32_fp8_e32 v[60:61], v133
	v_cvt_pk_f32_fp8_sdwa v[62:63], v133 src0_sel:WORD_1
	global_load_dwordx4 v[130:133], v76, s[42:43] offset:256
	v_pk_mul_f32 v[18:19], v[48:49], v[108:109]
	v_pk_fma_f32 v[18:19], v[50:51], v[110:111], v[18:19]
	v_pk_fma_f32 v[18:19], v[52:53], v[112:113], v[18:19]
	v_pk_fma_f32 v[18:19], v[54:55], v[114:115], v[18:19]
	v_pk_fma_f32 v[18:19], v[56:57], v[216:217], v[18:19]
	v_pk_fma_f32 v[18:19], v[58:59], v[218:219], v[18:19]
	v_pk_fma_f32 v[18:19], v[60:61], v[220:221], v[18:19]
	v_pk_fma_f32 v[18:19], v[62:63], v[222:223], v[18:19]
	s_waitcnt vmcnt(19)
	v_cvt_pk_f32_fp8_e32 v[48:49], v134
	v_cvt_pk_f32_fp8_sdwa v[50:51], v134 src0_sel:WORD_1
	v_cvt_pk_f32_fp8_e32 v[52:53], v135
	v_cvt_pk_f32_fp8_sdwa v[54:55], v135 src0_sel:WORD_1
	v_cvt_pk_f32_fp8_e32 v[56:57], v136
	v_cvt_pk_f32_fp8_sdwa v[58:59], v136 src0_sel:WORD_1
	v_cvt_pk_f32_fp8_e32 v[60:61], v137
	v_cvt_pk_f32_fp8_sdwa v[62:63], v137 src0_sel:WORD_1
	global_load_dwordx4 v[134:137], v77, s[42:43] offset:256
	v_pk_mul_f32 v[20:21], v[48:49], v[108:109]
	v_pk_fma_f32 v[20:21], v[50:51], v[110:111], v[20:21]
	v_pk_fma_f32 v[20:21], v[52:53], v[112:113], v[20:21]
	v_pk_fma_f32 v[20:21], v[54:55], v[114:115], v[20:21]
	v_pk_fma_f32 v[20:21], v[56:57], v[216:217], v[20:21]
	v_pk_fma_f32 v[20:21], v[58:59], v[218:219], v[20:21]
	v_pk_fma_f32 v[20:21], v[60:61], v[220:221], v[20:21]
	v_pk_fma_f32 v[20:21], v[62:63], v[222:223], v[20:21]
	s_waitcnt vmcnt(19)
;     ...
;     for (int m = 0; m < 16; m += 2) {
;         const u32x4_t a0 = *(const u32x4_t*)(hp + m * 64), a1 = *(const u32x4_t*)(hp + m * 64 + 64);
; #pragma unroll
;         for (int t = 0; t < NTL; ++t) FP8MM(a0, b0[t], acc[t]);
;         if (m + 2 < 16) {
; #pragma unroll
;             for (int t = 0; t < NTL; ++t) b0[t] = *(const u32x4_t*)(up[t] + (m + 2) * 64);
;         }
; #pragma unroll
;         for (int t = 0; t < NTL; ++t) FP8MM(a1, b1[t], acc[t]);
;         if (m + 3 < 16) {
; #pragma unroll
;             for (int t = 0; t < NTL; ++t) b1[t] = *(const u32x4_t*)(up[t] + (m + 3) * 64);
;         }
;     }
	v_cvt_pk_f32_fp8_e32 v[48:49], v138
	v_cvt_pk_f32_fp8_sdwa v[50:51], v138 src0_sel:WORD_1
	v_cvt_pk_f32_fp8_e32 v[52:53], v139
	v_cvt_pk_f32_fp8_sdwa v[54:55], v139 src0_sel:WORD_1
	v_cvt_pk_f32_fp8_e32 v[56:57], v140
	v_cvt_pk_f32_fp8_sdwa v[58:59], v140 src0_sel:WORD_1
	v_cvt_pk_f32_fp8_e32 v[60:61], v141
	v_cvt_pk_f32_fp8_sdwa v[62:63], v141 src0_sel:WORD_1
	global_load_dwordx4 v[138:141], v78, s[42:43] offset:256
	v_pk_mul_f32 v[22:23], v[48:49], v[108:109]
	v_pk_fma_f32 v[22:23], v[50:51], v[110:111], v[22:23]
	v_pk_fma_f32 v[22:23], v[52:53], v[112:113], v[22:23]
	v_pk_fma_f32 v[22:23], v[54:55], v[114:115], v[22:23]
	v_pk_fma_f32 v[22:23], v[56:57], v[216:217], v[22:23]
	v_pk_fma_f32 v[22:23], v[58:59], v[218:219], v[22:23]
	v_pk_fma_f32 v[22:23], v[60:61], v[220:221], v[22:23]
	v_pk_fma_f32 v[22:23], v[62:63], v[222:223], v[22:23]
	s_waitcnt vmcnt(19)
	v_cvt_pk_f32_fp8_e32 v[48:49], v142
	v_cvt_pk_f32_fp8_sdwa v[50:51], v142 src0_sel:WORD_1
	v_cvt_pk_f32_fp8_e32 v[52:53], v143
	v_cvt_pk_f32_fp8_sdwa v[54:55], v143 src0_sel:WORD_1
	v_cvt_pk_f32_fp8_e32 v[56:57], v144
	v_cvt_pk_f32_fp8_sdwa v[58:59], v144 src0_sel:WORD_1
	v_cvt_pk_f32_fp8_e32 v[60:61], v145
	v_cvt_pk_f32_fp8_sdwa v[62:63], v145 src0_sel:WORD_1
	global_load_dwordx4 v[142:145], v79, s[42:43] offset:256
	v_pk_mul_f32 v[24:25], v[48:49], v[108:109]
	v_pk_fma_f32 v[24:25], v[50:51], v[110:111], v[24:25]
	v_pk_fma_f32 v[24:25], v[52:53], v[112:113], v[24:25]
	v_pk_fma_f32 v[24:25], v[54:55], v[114:115], v[24:25]
	v_pk_fma_f32 v[24:25], v[56:57], v[216:217], v[24:25]
	v_pk_fma_f32 v[24:25], v[58:59], v[218:219], v[24:25]
	v_pk_fma_f32 v[24:25], v[60:61], v[220:221], v[24:25]
	v_pk_fma_f32 v[24:25], v[62:63], v[222:223], v[24:25]
	s_waitcnt vmcnt(19)
	v_cvt_pk_f32_fp8_e32 v[48:49], v146
	v_cvt_pk_f32_fp8_sdwa v[50:51], v146 src0_sel:WORD_1
	v_cvt_pk_f32_fp8_e32 v[52:53], v147
	v_cvt_pk_f32_fp8_sdwa v[54:55], v147 src0_sel:WORD_1
	v_cvt_pk_f32_fp8_e32 v[56:57], v148
	v_cvt_pk_f32_fp8_sdwa v[58:59], v148 src0_sel:WORD_1
	v_cvt_pk_f32_fp8_e32 v[60:61], v149
	v_cvt_pk_f32_fp8_sdwa v[62:63], v149 src0_sel:WORD_1
	global_load_dwordx4 v[146:149], v80, s[42:43] offset:256
	v_pk_mul_f32 v[26:27], v[48:49], v[108:109]
	v_pk_fma_f32 v[26:27], v[50:51], v[110:111], v[26:27]
	v_pk_fma_f32 v[26:27], v[52:53], v[112:113], v[26:27]
	v_pk_fma_f32 v[26:27], v[54:55], v[114:115], v[26:27]
	v_pk_fma_f32 v[26:27], v[56:57], v[216:217], v[26:27]
	v_pk_fma_f32 v[26:27], v[58:59], v[218:219], v[26:27]
	v_pk_fma_f32 v[26:27], v[60:61], v[220:221], v[26:27]
	v_pk_fma_f32 v[26:27], v[62:63], v[222:223], v[26:27]
	s_waitcnt vmcnt(19)
	v_cvt_pk_f32_fp8_e32 v[48:49], v150
	v_cvt_pk_f32_fp8_sdwa v[50:51], v150 src0_sel:WORD_1
	v_cvt_pk_f32_fp8_e32 v[52:53], v151
	v_cvt_pk_f32_fp8_sdwa v[54:55], v151 src0_sel:WORD_1
	v_cvt_pk_f32_fp8_e32 v[56:57], v152
	v_cvt_pk_f32_fp8_sdwa v[58:59], v152 src0_sel:WORD_1
	v_cvt_pk_f32_fp8_e32 v[60:61], v153
	v_cvt_pk_f32_fp8_sdwa v[62:63], v153 src0_sel:WORD_1
	global_load_dwordx4 v[150:153], v81, s[42:43] offset:256
	v_pk_mul_f32 v[28:29], v[48:49], v[108:109]
	v_pk_fma_f32 v[28:29], v[50:51], v[110:111], v[28:29]
	v_pk_fma_f32 v[28:29], v[52:53], v[112:113], v[28:29]
	v_pk_fma_f32 v[28:29], v[54:55], v[114:115], v[28:29]
	v_pk_fma_f32 v[28:29], v[56:57], v[216:217], v[28:29]
	v_pk_fma_f32 v[28:29], v[58:59], v[218:219], v[28:29]
	v_pk_fma_f32 v[28:29], v[60:61], v[220:221], v[28:29]
	v_pk_fma_f32 v[28:29], v[62:63], v[222:223], v[28:29]
	s_waitcnt vmcnt(19)
	v_cvt_pk_f32_fp8_e32 v[48:49], v154
	v_cvt_pk_f32_fp8_sdwa v[50:51], v154 src0_sel:WORD_1
	v_cvt_pk_f32_fp8_e32 v[52:53], v155
	v_cvt_pk_f32_fp8_sdwa v[54:55], v155 src0_sel:WORD_1
	v_cvt_pk_f32_fp8_e32 v[56:57], v156
	v_cvt_pk_f32_fp8_sdwa v[58:59], v156 src0_sel:WORD_1
	v_cvt_pk_f32_fp8_e32 v[60:61], v157
	v_cvt_pk_f32_fp8_sdwa v[62:63], v157 src0_sel:WORD_1
	global_load_dwordx4 v[154:157], v82, s[42:43] offset:256
	v_pk_mul_f32 v[30:31], v[48:49], v[108:109]
	v_pk_fma_f32 v[30:31], v[50:51], v[110:111], v[30:31]
	v_pk_fma_f32 v[30:31], v[52:53], v[112:113], v[30:31]
	v_pk_fma_f32 v[30:31], v[54:55], v[114:115], v[30:31]
	v_pk_fma_f32 v[30:31], v[56:57], v[216:217], v[30:31]
	v_pk_fma_f32 v[30:31], v[58:59], v[218:219], v[30:31]
	v_pk_fma_f32 v[30:31], v[60:61], v[220:221], v[30:31]
	v_pk_fma_f32 v[30:31], v[62:63], v[222:223], v[30:31]
	s_waitcnt vmcnt(19)
	v_cvt_pk_f32_fp8_e32 v[48:49], v158
	v_cvt_pk_f32_fp8_sdwa v[50:51], v158 src0_sel:WORD_1
	v_cvt_pk_f32_fp8_e32 v[52:53], v159
	v_cvt_pk_f32_fp8_sdwa v[54:55], v159 src0_sel:WORD_1
	v_cvt_pk_f32_fp8_e32 v[56:57], v160
	v_cvt_pk_f32_fp8_sdwa v[58:59], v160 src0_sel:WORD_1
	v_cvt_pk_f32_fp8_e32 v[60:61], v161
	v_cvt_pk_f32_fp8_sdwa v[62:63], v161 src0_sel:WORD_1
	global_load_dwordx4 v[158:161], v83, s[42:43] offset:256
	v_pk_mul_f32 v[32:33], v[48:49], v[108:109]
	v_pk_fma_f32 v[32:33], v[50:51], v[110:111], v[32:33]
	v_pk_fma_f32 v[32:33], v[52:53], v[112:113], v[32:33]
	v_pk_fma_f32 v[32:33], v[54:55], v[114:115], v[32:33]
	v_pk_fma_f32 v[32:33], v[56:57], v[216:217], v[32:33]
	v_pk_fma_f32 v[32:33], v[58:59], v[218:219], v[32:33]
	v_pk_fma_f32 v[32:33], v[60:61], v[220:221], v[32:33]
	v_pk_fma_f32 v[32:33], v[62:63], v[222:223], v[32:33]
	s_waitcnt vmcnt(28)
;     ...
;     for (int m = 0; m < 16; m += 2) {
;         const u32x4_t a0 = *(const u32x4_t*)(hp + m * 64), a1 = *(const u32x4_t*)(hp + m * 64 + 64);
; #pragma unroll
;         for (int t = 0; t < NTL; ++t) FP8MM(a0, b0[t], acc[t]);
;         if (m + 2 < 16) {
; #pragma unroll
;             for (int t = 0; t < NTL; ++t) b0[t] = *(const u32x4_t*)(up[t] + (m + 2) * 64);
;         }
; #pragma unroll
;         for (int t = 0; t < NTL; ++t) FP8MM(a1, b1[t], acc[t]);
;         if (m + 3 < 16) {
; #pragma unroll
;             for (int t = 0; t < NTL; ++t) b1[t] = *(const u32x4_t*)(up[t] + (m + 3) * 64);
;         }
;     }
	v_cvt_pk_f32_fp8_e32 v[108:109], v96
	v_cvt_pk_f32_fp8_sdwa v[110:111], v96 src0_sel:WORD_1
	v_cvt_pk_f32_fp8_e32 v[112:113], v97
	v_cvt_pk_f32_fp8_sdwa v[114:115], v97 src0_sel:WORD_1
	v_cvt_pk_f32_fp8_e32 v[216:217], v98
	v_cvt_pk_f32_fp8_sdwa v[218:219], v98 src0_sel:WORD_1
	v_cvt_pk_f32_fp8_e32 v[220:221], v99
	v_cvt_pk_f32_fp8_sdwa v[222:223], v99 src0_sel:WORD_1
	v_cvt_pk_f32_fp8_e32 v[48:49], v104
	v_cvt_pk_f32_fp8_sdwa v[50:51], v104 src0_sel:WORD_1
	v_cvt_pk_f32_fp8_e32 v[52:53], v105
	v_cvt_pk_f32_fp8_sdwa v[54:55], v105 src0_sel:WORD_1
	v_cvt_pk_f32_fp8_e32 v[56:57], v106
	v_cvt_pk_f32_fp8_sdwa v[58:59], v106 src0_sel:WORD_1
	v_cvt_pk_f32_fp8_e32 v[60:61], v107
	v_cvt_pk_f32_fp8_sdwa v[62:63], v107 src0_sel:WORD_1
	v_pk_fma_f32 v[108:109], v[48:49], v[44:45], v[108:109]
	v_pk_fma_f32 v[110:111], v[50:51], v[44:45], v[110:111]
	v_pk_fma_f32 v[112:113], v[52:53], v[44:45], v[112:113]
	v_pk_fma_f32 v[114:115], v[54:55], v[44:45], v[114:115]
	v_pk_fma_f32 v[216:217], v[56:57], v[44:45], v[216:217]
	v_pk_fma_f32 v[218:219], v[58:59], v[44:45], v[218:219]
	v_pk_fma_f32 v[220:221], v[60:61], v[44:45], v[220:221]
	v_pk_fma_f32 v[222:223], v[62:63], v[44:45], v[222:223]
	global_load_dwordx4 v[96:99], v4, s[44:45] offset:384
	global_load_dwordx4 v[104:107], v8, s[44:45] offset:384
	s_waitcnt vmcnt(21)
	v_cvt_pk_f32_fp8_e32 v[48:49], v162
	v_cvt_pk_f32_fp8_sdwa v[50:51], v162 src0_sel:WORD_1
	v_cvt_pk_f32_fp8_e32 v[52:53], v163
	v_cvt_pk_f32_fp8_sdwa v[54:55], v163 src0_sel:WORD_1
	v_cvt_pk_f32_fp8_e32 v[56:57], v164
	v_cvt_pk_f32_fp8_sdwa v[58:59], v164 src0_sel:WORD_1
	v_cvt_pk_f32_fp8_e32 v[60:61], v165
	v_cvt_pk_f32_fp8_sdwa v[62:63], v165 src0_sel:WORD_1
	global_load_dwordx4 v[162:165], v76, s[42:43] offset:384
	v_pk_fma_f32 v[18:19], v[48:49], v[108:109], v[18:19]
	v_pk_fma_f32 v[18:19], v[50:51], v[110:111], v[18:19]
	v_pk_fma_f32 v[18:19], v[52:53], v[112:113], v[18:19]
	v_pk_fma_f32 v[18:19], v[54:55], v[114:115], v[18:19]
	v_pk_fma_f32 v[18:19], v[56:57], v[216:217], v[18:19]
	v_pk_fma_f32 v[18:19], v[58:59], v[218:219], v[18:19]
	v_pk_fma_f32 v[18:19], v[60:61], v[220:221], v[18:19]
	v_pk_fma_f32 v[18:19], v[62:63], v[222:223], v[18:19]
	s_waitcnt vmcnt(21)
	v_cvt_pk_f32_fp8_e32 v[48:49], v166
	v_cvt_pk_f32_fp8_sdwa v[50:51], v166 src0_sel:WORD_1
	v_cvt_pk_f32_fp8_e32 v[52:53], v167
	v_cvt_pk_f32_fp8_sdwa v[54:55], v167 src0_sel:WORD_1
	v_cvt_pk_f32_fp8_e32 v[56:57], v168
	v_cvt_pk_f32_fp8_sdwa v[58:59], v168 src0_sel:WORD_1
	v_cvt_pk_f32_fp8_e32 v[60:61], v169
	v_cvt_pk_f32_fp8_sdwa v[62:63], v169 src0_sel:WORD_1
	global_load_dwordx4 v[166:169], v77, s[42:43] offset:384
	v_pk_fma_f32 v[20:21], v[48:49], v[108:109], v[20:21]
	v_pk_fma_f32 v[20:21], v[50:51], v[110:111], v[20:21]
	v_pk_fma_f32 v[20:21], v[52:53], v[112:113], v[20:21]
	v_pk_fma_f32 v[20:21], v[54:55], v[114:115], v[20:21]
	v_pk_fma_f32 v[20:21], v[56:57], v[216:217], v[20:21]
	v_pk_fma_f32 v[20:21], v[58:59], v[218:219], v[20:21]
	v_pk_fma_f32 v[20:21], v[60:61], v[220:221], v[20:21]
	v_pk_fma_f32 v[20:21], v[62:63], v[222:223], v[20:21]
	s_waitcnt vmcnt(21)
	v_cvt_pk_f32_fp8_e32 v[48:49], v170
	v_cvt_pk_f32_fp8_sdwa v[50:51], v170 src0_sel:WORD_1
	v_cvt_pk_f32_fp8_e32 v[52:53], v171
	v_cvt_pk_f32_fp8_sdwa v[54:55], v171 src0_sel:WORD_1
	v_cvt_pk_f32_fp8_e32 v[56:57], v172
	v_cvt_pk_f32_fp8_sdwa v[58:59], v172 src0_sel:WORD_1
	v_cvt_pk_f32_fp8_e32 v[60:61], v173
	v_cvt_pk_f32_fp8_sdwa v[62:63], v173 src0_sel:WORD_1
	global_load_dwordx4 v[170:173], v78, s[42:43] offset:384
	v_pk_fma_f32 v[22:23], v[48:49], v[108:109], v[22:23]
	v_pk_fma_f32 v[22:23], v[50:51], v[110:111], v[22:23]
	v_pk_fma_f32 v[22:23], v[52:53], v[112:113], v[22:23]
	v_pk_fma_f32 v[22:23], v[54:55], v[114:115], v[22:23]
	v_pk_fma_f32 v[22:23], v[56:57], v[216:217], v[22:23]
	v_pk_fma_f32 v[22:23], v[58:59], v[218:219], v[22:23]
	v_pk_fma_f32 v[22:23], v[60:61], v[220:221], v[22:23]
	v_pk_fma_f32 v[22:23], v[62:63], v[222:223], v[22:23]
	s_waitcnt vmcnt(21)
	v_cvt_pk_f32_fp8_e32 v[48:49], v180
	v_cvt_pk_f32_fp8_sdwa v[50:51], v180 src0_sel:WORD_1
	v_cvt_pk_f32_fp8_e32 v[52:53], v181
	v_cvt_pk_f32_fp8_sdwa v[54:55], v181 src0_sel:WORD_1
	v_cvt_pk_f32_fp8_e32 v[56:57], v182
	v_cvt_pk_f32_fp8_sdwa v[58:59], v182 src0_sel:WORD_1
	v_cvt_pk_f32_fp8_e32 v[60:61], v183
	v_cvt_pk_f32_fp8_sdwa v[62:63], v183 src0_sel:WORD_1
	global_load_dwordx4 v[180:183], v79, s[42:43] offset:384
	v_pk_fma_f32 v[24:25], v[48:49], v[108:109], v[24:25]
	v_pk_fma_f32 v[24:25], v[50:51], v[110:111], v[24:25]
	v_pk_fma_f32 v[24:25], v[52:53], v[112:113], v[24:25]
	v_pk_fma_f32 v[24:25], v[54:55], v[114:115], v[24:25]
	v_pk_fma_f32 v[24:25], v[56:57], v[216:217], v[24:25]
	v_pk_fma_f32 v[24:25], v[58:59], v[218:219], v[24:25]
	v_pk_fma_f32 v[24:25], v[60:61], v[220:221], v[24:25]
	v_pk_fma_f32 v[24:25], v[62:63], v[222:223], v[24:25]
	s_waitcnt vmcnt(21)
	v_cvt_pk_f32_fp8_e32 v[48:49], v184
	v_cvt_pk_f32_fp8_sdwa v[50:51], v184 src0_sel:WORD_1
	v_cvt_pk_f32_fp8_e32 v[52:53], v185
	v_cvt_pk_f32_fp8_sdwa v[54:55], v185 src0_sel:WORD_1
	v_cvt_pk_f32_fp8_e32 v[56:57], v186
	v_cvt_pk_f32_fp8_sdwa v[58:59], v186 src0_sel:WORD_1
	v_cvt_pk_f32_fp8_e32 v[60:61], v187
	v_cvt_pk_f32_fp8_sdwa v[62:63], v187 src0_sel:WORD_1
	global_load_dwordx4 v[184:187], v80, s[42:43] offset:384
	v_pk_fma_f32 v[26:27], v[48:49], v[108:109], v[26:27]
	v_pk_fma_f32 v[26:27], v[50:51], v[110:111], v[26:27]
	v_pk_fma_f32 v[26:27], v[52:53], v[112:113], v[26:27]
	v_pk_fma_f32 v[26:27], v[54:55], v[114:115], v[26:27]
	v_pk_fma_f32 v[26:27], v[56:57], v[216:217], v[26:27]
	v_pk_fma_f32 v[26:27], v[58:59], v[218:219], v[26:27]
	v_pk_fma_f32 v[26:27], v[60:61], v[220:221], v[26:27]
	v_pk_fma_f32 v[26:27], v[62:63], v[222:223], v[26:27]
	s_waitcnt vmcnt(21)
;     ...
;     for (int m = 0; m < 16; m += 2) {
;         const u32x4_t a0 = *(const u32x4_t*)(hp + m * 64), a1 = *(const u32x4_t*)(hp + m * 64 + 64);
; #pragma unroll
;         for (int t = 0; t < NTL; ++t) FP8MM(a0, b0[t], acc[t]);
;         if (m + 2 < 16) {
; #pragma unroll
;             for (int t = 0; t < NTL; ++t) b0[t] = *(const u32x4_t*)(up[t] + (m + 2) * 64);
;         }
; #pragma unroll
;         for (int t = 0; t < NTL; ++t) FP8MM(a1, b1[t], acc[t]);
;         if (m + 3 < 16) {
; #pragma unroll
;             for (int t = 0; t < NTL; ++t) b1[t] = *(const u32x4_t*)(up[t] + (m + 3) * 64);
;         }
;     }
	v_cvt_pk_f32_fp8_e32 v[48:49], v188
	v_cvt_pk_f32_fp8_sdwa v[50:51], v188 src0_sel:WORD_1
	v_cvt_pk_f32_fp8_e32 v[52:53], v189
	v_cvt_pk_f32_fp8_sdwa v[54:55], v189 src0_sel:WORD_1
	v_cvt_pk_f32_fp8_e32 v[56:57], v190
	v_cvt_pk_f32_fp8_sdwa v[58:59], v190 src0_sel:WORD_1
	v_cvt_pk_f32_fp8_e32 v[60:61], v191
	v_cvt_pk_f32_fp8_sdwa v[62:63], v191 src0_sel:WORD_1
	global_load_dwordx4 v[188:191], v81, s[42:43] offset:384
	v_pk_fma_f32 v[28:29], v[48:49], v[108:109], v[28:29]
	v_pk_fma_f32 v[28:29], v[50:51], v[110:111], v[28:29]
	v_pk_fma_f32 v[28:29], v[52:53], v[112:113], v[28:29]
	v_pk_fma_f32 v[28:29], v[54:55], v[114:115], v[28:29]
	v_pk_fma_f32 v[28:29], v[56:57], v[216:217], v[28:29]
	v_pk_fma_f32 v[28:29], v[58:59], v[218:219], v[28:29]
	v_pk_fma_f32 v[28:29], v[60:61], v[220:221], v[28:29]
	v_pk_fma_f32 v[28:29], v[62:63], v[222:223], v[28:29]
	s_waitcnt vmcnt(21)
	v_cvt_pk_f32_fp8_e32 v[48:49], v192
	v_cvt_pk_f32_fp8_sdwa v[50:51], v192 src0_sel:WORD_1
	v_cvt_pk_f32_fp8_e32 v[52:53], v193
	v_cvt_pk_f32_fp8_sdwa v[54:55], v193 src0_sel:WORD_1
	v_cvt_pk_f32_fp8_e32 v[56:57], v194
	v_cvt_pk_f32_fp8_sdwa v[58:59], v194 src0_sel:WORD_1
	v_cvt_pk_f32_fp8_e32 v[60:61], v195
	v_cvt_pk_f32_fp8_sdwa v[62:63], v195 src0_sel:WORD_1
	global_load_dwordx4 v[192:195], v82, s[42:43] offset:384
	v_pk_fma_f32 v[30:31], v[48:49], v[108:109], v[30:31]
	v_pk_fma_f32 v[30:31], v[50:51], v[110:111], v[30:31]
	v_pk_fma_f32 v[30:31], v[52:53], v[112:113], v[30:31]
	v_pk_fma_f32 v[30:31], v[54:55], v[114:115], v[30:31]
	v_pk_fma_f32 v[30:31], v[56:57], v[216:217], v[30:31]
	v_pk_fma_f32 v[30:31], v[58:59], v[218:219], v[30:31]
	v_pk_fma_f32 v[30:31], v[60:61], v[220:221], v[30:31]
	v_pk_fma_f32 v[30:31], v[62:63], v[222:223], v[30:31]
	s_waitcnt vmcnt(21)
	v_cvt_pk_f32_fp8_e32 v[48:49], v196
	v_cvt_pk_f32_fp8_sdwa v[50:51], v196 src0_sel:WORD_1
	v_cvt_pk_f32_fp8_e32 v[52:53], v197
	v_cvt_pk_f32_fp8_sdwa v[54:55], v197 src0_sel:WORD_1
	v_cvt_pk_f32_fp8_e32 v[56:57], v198
	v_cvt_pk_f32_fp8_sdwa v[58:59], v198 src0_sel:WORD_1
	v_cvt_pk_f32_fp8_e32 v[60:61], v199
	v_cvt_pk_f32_fp8_sdwa v[62:63], v199 src0_sel:WORD_1
	global_load_dwordx4 v[196:199], v83, s[42:43] offset:384
	v_pk_fma_f32 v[32:33], v[48:49], v[108:109], v[32:33]
	v_pk_fma_f32 v[32:33], v[50:51], v[110:111], v[32:33]
	v_pk_fma_f32 v[32:33], v[52:53], v[112:113], v[32:33]
	v_pk_fma_f32 v[32:33], v[54:55], v[114:115], v[32:33]
	v_pk_fma_f32 v[32:33], v[56:57], v[216:217], v[32:33]
	v_pk_fma_f32 v[32:33], v[58:59], v[218:219], v[32:33]
	v_pk_fma_f32 v[32:33], v[60:61], v[220:221], v[32:33]
	v_pk_fma_f32 v[32:33], v[62:63], v[222:223], v[32:33]
	s_waitcnt vmcnt(18)
	v_cvt_pk_f32_fp8_e32 v[108:109], v88
	v_cvt_pk_f32_fp8_sdwa v[110:111], v88 src0_sel:WORD_1
	v_cvt_pk_f32_fp8_e32 v[112:113], v89
	v_cvt_pk_f32_fp8_sdwa v[114:115], v89 src0_sel:WORD_1
	v_cvt_pk_f32_fp8_e32 v[216:217], v90
	v_cvt_pk_f32_fp8_sdwa v[218:219], v90 src0_sel:WORD_1
	v_cvt_pk_f32_fp8_e32 v[220:221], v91
	v_cvt_pk_f32_fp8_sdwa v[222:223], v91 src0_sel:WORD_1
	v_cvt_pk_f32_fp8_e32 v[48:49], v92
	v_cvt_pk_f32_fp8_sdwa v[50:51], v92 src0_sel:WORD_1
	v_cvt_pk_f32_fp8_e32 v[52:53], v93
	v_cvt_pk_f32_fp8_sdwa v[54:55], v93 src0_sel:WORD_1
	v_cvt_pk_f32_fp8_e32 v[56:57], v94
	v_cvt_pk_f32_fp8_sdwa v[58:59], v94 src0_sel:WORD_1
	v_cvt_pk_f32_fp8_e32 v[60:61], v95
	v_cvt_pk_f32_fp8_sdwa v[62:63], v95 src0_sel:WORD_1
	v_pk_fma_f32 v[108:109], v[48:49], v[44:45], v[108:109]
	v_pk_fma_f32 v[110:111], v[50:51], v[44:45], v[110:111]
	v_pk_fma_f32 v[112:113], v[52:53], v[44:45], v[112:113]
	v_pk_fma_f32 v[114:115], v[54:55], v[44:45], v[114:115]
	v_pk_fma_f32 v[216:217], v[56:57], v[44:45], v[216:217]
	v_pk_fma_f32 v[218:219], v[58:59], v[44:45], v[218:219]
	v_pk_fma_f32 v[220:221], v[60:61], v[44:45], v[220:221]
	v_pk_fma_f32 v[222:223], v[62:63], v[44:45], v[222:223]
	global_load_dwordx4 v[88:91], v4, s[44:45] offset:512
	global_load_dwordx4 v[92:95], v8, s[44:45] offset:512
	s_waitcnt vmcnt(19)
	v_cvt_pk_f32_fp8_e32 v[48:49], v130
	v_cvt_pk_f32_fp8_sdwa v[50:51], v130 src0_sel:WORD_1
	v_cvt_pk_f32_fp8_e32 v[52:53], v131
	v_cvt_pk_f32_fp8_sdwa v[54:55], v131 src0_sel:WORD_1
	v_cvt_pk_f32_fp8_e32 v[56:57], v132
	v_cvt_pk_f32_fp8_sdwa v[58:59], v132 src0_sel:WORD_1
	v_cvt_pk_f32_fp8_e32 v[60:61], v133
	v_cvt_pk_f32_fp8_sdwa v[62:63], v133 src0_sel:WORD_1
	global_load_dwordx4 v[130:133], v76, s[42:43] offset:512
	v_pk_fma_f32 v[18:19], v[48:49], v[108:109], v[18:19]
	v_pk_fma_f32 v[18:19], v[50:51], v[110:111], v[18:19]
	v_pk_fma_f32 v[18:19], v[52:53], v[112:113], v[18:19]
	v_pk_fma_f32 v[18:19], v[54:55], v[114:115], v[18:19]
	v_pk_fma_f32 v[18:19], v[56:57], v[216:217], v[18:19]
	v_pk_fma_f32 v[18:19], v[58:59], v[218:219], v[18:19]
	v_pk_fma_f32 v[18:19], v[60:61], v[220:221], v[18:19]
	v_pk_fma_f32 v[18:19], v[62:63], v[222:223], v[18:19]
	s_waitcnt vmcnt(19)
	v_cvt_pk_f32_fp8_e32 v[48:49], v134
	v_cvt_pk_f32_fp8_sdwa v[50:51], v134 src0_sel:WORD_1
	v_cvt_pk_f32_fp8_e32 v[52:53], v135
	v_cvt_pk_f32_fp8_sdwa v[54:55], v135 src0_sel:WORD_1
	v_cvt_pk_f32_fp8_e32 v[56:57], v136
	v_cvt_pk_f32_fp8_sdwa v[58:59], v136 src0_sel:WORD_1
	v_cvt_pk_f32_fp8_e32 v[60:61], v137
	v_cvt_pk_f32_fp8_sdwa v[62:63], v137 src0_sel:WORD_1
	global_load_dwordx4 v[134:137], v77, s[42:43] offset:512
	v_pk_fma_f32 v[20:21], v[48:49], v[108:109], v[20:21]
	v_pk_fma_f32 v[20:21], v[50:51], v[110:111], v[20:21]
	v_pk_fma_f32 v[20:21], v[52:53], v[112:113], v[20:21]
	v_pk_fma_f32 v[20:21], v[54:55], v[114:115], v[20:21]
	v_pk_fma_f32 v[20:21], v[56:57], v[216:217], v[20:21]
	v_pk_fma_f32 v[20:21], v[58:59], v[218:219], v[20:21]
	v_pk_fma_f32 v[20:21], v[60:61], v[220:221], v[20:21]
	v_pk_fma_f32 v[20:21], v[62:63], v[222:223], v[20:21]
	s_waitcnt vmcnt(19)
;     ...
;     for (int m = 0; m < 16; m += 2) {
;         const u32x4_t a0 = *(const u32x4_t*)(hp + m * 64), a1 = *(const u32x4_t*)(hp + m * 64 + 64);
; #pragma unroll
;         for (int t = 0; t < NTL; ++t) FP8MM(a0, b0[t], acc[t]);
;         if (m + 2 < 16) {
; #pragma unroll
;             for (int t = 0; t < NTL; ++t) b0[t] = *(const u32x4_t*)(up[t] + (m + 2) * 64);
;         }
; #pragma unroll
;         for (int t = 0; t < NTL; ++t) FP8MM(a1, b1[t], acc[t]);
;         if (m + 3 < 16) {
; #pragma unroll
;             for (int t = 0; t < NTL; ++t) b1[t] = *(const u32x4_t*)(up[t] + (m + 3) * 64);
;         }
;     }
	v_cvt_pk_f32_fp8_e32 v[48:49], v138
	v_cvt_pk_f32_fp8_sdwa v[50:51], v138 src0_sel:WORD_1
	v_cvt_pk_f32_fp8_e32 v[52:53], v139
	v_cvt_pk_f32_fp8_sdwa v[54:55], v139 src0_sel:WORD_1
	v_cvt_pk_f32_fp8_e32 v[56:57], v140
	v_cvt_pk_f32_fp8_sdwa v[58:59], v140 src0_sel:WORD_1
	v_cvt_pk_f32_fp8_e32 v[60:61], v141
	v_cvt_pk_f32_fp8_sdwa v[62:63], v141 src0_sel:WORD_1
	global_load_dwordx4 v[138:141], v78, s[42:43] offset:512
	v_pk_fma_f32 v[22:23], v[48:49], v[108:109], v[22:23]
	v_pk_fma_f32 v[22:23], v[50:51], v[110:111], v[22:23]
	v_pk_fma_f32 v[22:23], v[52:53], v[112:113], v[22:23]
	v_pk_fma_f32 v[22:23], v[54:55], v[114:115], v[22:23]
	v_pk_fma_f32 v[22:23], v[56:57], v[216:217], v[22:23]
	v_pk_fma_f32 v[22:23], v[58:59], v[218:219], v[22:23]
	v_pk_fma_f32 v[22:23], v[60:61], v[220:221], v[22:23]
	v_pk_fma_f32 v[22:23], v[62:63], v[222:223], v[22:23]
	s_waitcnt vmcnt(19)
	v_cvt_pk_f32_fp8_e32 v[48:49], v142
	v_cvt_pk_f32_fp8_sdwa v[50:51], v142 src0_sel:WORD_1
	v_cvt_pk_f32_fp8_e32 v[52:53], v143
	v_cvt_pk_f32_fp8_sdwa v[54:55], v143 src0_sel:WORD_1
	v_cvt_pk_f32_fp8_e32 v[56:57], v144
	v_cvt_pk_f32_fp8_sdwa v[58:59], v144 src0_sel:WORD_1
	v_cvt_pk_f32_fp8_e32 v[60:61], v145
	v_cvt_pk_f32_fp8_sdwa v[62:63], v145 src0_sel:WORD_1
	global_load_dwordx4 v[142:145], v79, s[42:43] offset:512
	v_pk_fma_f32 v[24:25], v[48:49], v[108:109], v[24:25]
	v_pk_fma_f32 v[24:25], v[50:51], v[110:111], v[24:25]
	v_pk_fma_f32 v[24:25], v[52:53], v[112:113], v[24:25]
	v_pk_fma_f32 v[24:25], v[54:55], v[114:115], v[24:25]
	v_pk_fma_f32 v[24:25], v[56:57], v[216:217], v[24:25]
	v_pk_fma_f32 v[24:25], v[58:59], v[218:219], v[24:25]
	v_pk_fma_f32 v[24:25], v[60:61], v[220:221], v[24:25]
	v_pk_fma_f32 v[24:25], v[62:63], v[222:223], v[24:25]
	s_waitcnt vmcnt(19)
	v_cvt_pk_f32_fp8_e32 v[48:49], v146
	v_cvt_pk_f32_fp8_sdwa v[50:51], v146 src0_sel:WORD_1
	v_cvt_pk_f32_fp8_e32 v[52:53], v147
	v_cvt_pk_f32_fp8_sdwa v[54:55], v147 src0_sel:WORD_1
	v_cvt_pk_f32_fp8_e32 v[56:57], v148
	v_cvt_pk_f32_fp8_sdwa v[58:59], v148 src0_sel:WORD_1
	v_cvt_pk_f32_fp8_e32 v[60:61], v149
	v_cvt_pk_f32_fp8_sdwa v[62:63], v149 src0_sel:WORD_1
	global_load_dwordx4 v[146:149], v80, s[42:43] offset:512
	v_pk_fma_f32 v[26:27], v[48:49], v[108:109], v[26:27]
	v_pk_fma_f32 v[26:27], v[50:51], v[110:111], v[26:27]
	v_pk_fma_f32 v[26:27], v[52:53], v[112:113], v[26:27]
	v_pk_fma_f32 v[26:27], v[54:55], v[114:115], v[26:27]
	v_pk_fma_f32 v[26:27], v[56:57], v[216:217], v[26:27]
	v_pk_fma_f32 v[26:27], v[58:59], v[218:219], v[26:27]
	v_pk_fma_f32 v[26:27], v[60:61], v[220:221], v[26:27]
	v_pk_fma_f32 v[26:27], v[62:63], v[222:223], v[26:27]
	s_waitcnt vmcnt(19)
	v_cvt_pk_f32_fp8_e32 v[48:49], v150
	v_cvt_pk_f32_fp8_sdwa v[50:51], v150 src0_sel:WORD_1
	v_cvt_pk_f32_fp8_e32 v[52:53], v151
	v_cvt_pk_f32_fp8_sdwa v[54:55], v151 src0_sel:WORD_1
	v_cvt_pk_f32_fp8_e32 v[56:57], v152
	v_cvt_pk_f32_fp8_sdwa v[58:59], v152 src0_sel:WORD_1
	v_cvt_pk_f32_fp8_e32 v[60:61], v153
	v_cvt_pk_f32_fp8_sdwa v[62:63], v153 src0_sel:WORD_1
	global_load_dwordx4 v[150:153], v81, s[42:43] offset:512
	v_pk_fma_f32 v[28:29], v[48:49], v[108:109], v[28:29]
	v_pk_fma_f32 v[28:29], v[50:51], v[110:111], v[28:29]
	v_pk_fma_f32 v[28:29], v[52:53], v[112:113], v[28:29]
	v_pk_fma_f32 v[28:29], v[54:55], v[114:115], v[28:29]
	v_pk_fma_f32 v[28:29], v[56:57], v[216:217], v[28:29]
	v_pk_fma_f32 v[28:29], v[58:59], v[218:219], v[28:29]
	v_pk_fma_f32 v[28:29], v[60:61], v[220:221], v[28:29]
	v_pk_fma_f32 v[28:29], v[62:63], v[222:223], v[28:29]
	s_waitcnt vmcnt(19)
	v_cvt_pk_f32_fp8_e32 v[48:49], v154
	v_cvt_pk_f32_fp8_sdwa v[50:51], v154 src0_sel:WORD_1
	v_cvt_pk_f32_fp8_e32 v[52:53], v155
	v_cvt_pk_f32_fp8_sdwa v[54:55], v155 src0_sel:WORD_1
	v_cvt_pk_f32_fp8_e32 v[56:57], v156
	v_cvt_pk_f32_fp8_sdwa v[58:59], v156 src0_sel:WORD_1
	v_cvt_pk_f32_fp8_e32 v[60:61], v157
	v_cvt_pk_f32_fp8_sdwa v[62:63], v157 src0_sel:WORD_1
	global_load_dwordx4 v[154:157], v82, s[42:43] offset:512
	v_pk_fma_f32 v[30:31], v[48:49], v[108:109], v[30:31]
	v_pk_fma_f32 v[30:31], v[50:51], v[110:111], v[30:31]
	v_pk_fma_f32 v[30:31], v[52:53], v[112:113], v[30:31]
	v_pk_fma_f32 v[30:31], v[54:55], v[114:115], v[30:31]
	v_pk_fma_f32 v[30:31], v[56:57], v[216:217], v[30:31]
	v_pk_fma_f32 v[30:31], v[58:59], v[218:219], v[30:31]
	v_pk_fma_f32 v[30:31], v[60:61], v[220:221], v[30:31]
	v_pk_fma_f32 v[30:31], v[62:63], v[222:223], v[30:31]
	s_waitcnt vmcnt(19)
	v_cvt_pk_f32_fp8_e32 v[48:49], v158
	v_cvt_pk_f32_fp8_sdwa v[50:51], v158 src0_sel:WORD_1
	v_cvt_pk_f32_fp8_e32 v[52:53], v159
	v_cvt_pk_f32_fp8_sdwa v[54:55], v159 src0_sel:WORD_1
	v_cvt_pk_f32_fp8_e32 v[56:57], v160
	v_cvt_pk_f32_fp8_sdwa v[58:59], v160 src0_sel:WORD_1
	v_cvt_pk_f32_fp8_e32 v[60:61], v161
	v_cvt_pk_f32_fp8_sdwa v[62:63], v161 src0_sel:WORD_1
	global_load_dwordx4 v[158:161], v83, s[42:43] offset:512
	v_pk_fma_f32 v[32:33], v[48:49], v[108:109], v[32:33]
	v_pk_fma_f32 v[32:33], v[50:51], v[110:111], v[32:33]
	v_pk_fma_f32 v[32:33], v[52:53], v[112:113], v[32:33]
	v_pk_fma_f32 v[32:33], v[54:55], v[114:115], v[32:33]
	v_pk_fma_f32 v[32:33], v[56:57], v[216:217], v[32:33]
	v_pk_fma_f32 v[32:33], v[58:59], v[218:219], v[32:33]
	v_pk_fma_f32 v[32:33], v[60:61], v[220:221], v[32:33]
	v_pk_fma_f32 v[32:33], v[62:63], v[222:223], v[32:33]
	s_waitcnt vmcnt(18)
;     ...
;     for (int m = 0; m < 16; m += 2) {
;         const u32x4_t a0 = *(const u32x4_t*)(hp + m * 64), a1 = *(const u32x4_t*)(hp + m * 64 + 64);
; #pragma unroll
;         for (int t = 0; t < NTL; ++t) FP8MM(a0, b0[t], acc[t]);
;         if (m + 2 < 16) {
; #pragma unroll
;             for (int t = 0; t < NTL; ++t) b0[t] = *(const u32x4_t*)(up[t] + (m + 2) * 64);
;         }
; #pragma unroll
;         for (int t = 0; t < NTL; ++t) FP8MM(a1, b1[t], acc[t]);
;         if (m + 3 < 16) {
; #pragma unroll
;             for (int t = 0; t < NTL; ++t) b1[t] = *(const u32x4_t*)(up[t] + (m + 3) * 64);
;         }
;     }
	v_cvt_pk_f32_fp8_e32 v[108:109], v96
	v_cvt_pk_f32_fp8_sdwa v[110:111], v96 src0_sel:WORD_1
	v_cvt_pk_f32_fp8_e32 v[112:113], v97
	v_cvt_pk_f32_fp8_sdwa v[114:115], v97 src0_sel:WORD_1
	v_cvt_pk_f32_fp8_e32 v[216:217], v98
	v_cvt_pk_f32_fp8_sdwa v[218:219], v98 src0_sel:WORD_1
	v_cvt_pk_f32_fp8_e32 v[220:221], v99
	v_cvt_pk_f32_fp8_sdwa v[222:223], v99 src0_sel:WORD_1
	v_cvt_pk_f32_fp8_e32 v[48:49], v104
	v_cvt_pk_f32_fp8_sdwa v[50:51], v104 src0_sel:WORD_1
	v_cvt_pk_f32_fp8_e32 v[52:53], v105
	v_cvt_pk_f32_fp8_sdwa v[54:55], v105 src0_sel:WORD_1
	v_cvt_pk_f32_fp8_e32 v[56:57], v106
	v_cvt_pk_f32_fp8_sdwa v[58:59], v106 src0_sel:WORD_1
	v_cvt_pk_f32_fp8_e32 v[60:61], v107
	v_cvt_pk_f32_fp8_sdwa v[62:63], v107 src0_sel:WORD_1
	v_pk_fma_f32 v[108:109], v[48:49], v[44:45], v[108:109]
	v_pk_fma_f32 v[110:111], v[50:51], v[44:45], v[110:111]
	v_pk_fma_f32 v[112:113], v[52:53], v[44:45], v[112:113]
	v_pk_fma_f32 v[114:115], v[54:55], v[44:45], v[114:115]
	v_pk_fma_f32 v[216:217], v[56:57], v[44:45], v[216:217]
	v_pk_fma_f32 v[218:219], v[58:59], v[44:45], v[218:219]
	v_pk_fma_f32 v[220:221], v[60:61], v[44:45], v[220:221]
	v_pk_fma_f32 v[222:223], v[62:63], v[44:45], v[222:223]
	global_load_dwordx4 v[96:99], v4, s[44:45] offset:640
	global_load_dwordx4 v[104:107], v8, s[44:45] offset:640
	s_waitcnt vmcnt(19)
	v_cvt_pk_f32_fp8_e32 v[48:49], v162
	v_cvt_pk_f32_fp8_sdwa v[50:51], v162 src0_sel:WORD_1
	v_cvt_pk_f32_fp8_e32 v[52:53], v163
	v_cvt_pk_f32_fp8_sdwa v[54:55], v163 src0_sel:WORD_1
	v_cvt_pk_f32_fp8_e32 v[56:57], v164
	v_cvt_pk_f32_fp8_sdwa v[58:59], v164 src0_sel:WORD_1
	v_cvt_pk_f32_fp8_e32 v[60:61], v165
	v_cvt_pk_f32_fp8_sdwa v[62:63], v165 src0_sel:WORD_1
	global_load_dwordx4 v[162:165], v76, s[42:43] offset:640
	v_pk_fma_f32 v[18:19], v[48:49], v[108:109], v[18:19]
	v_pk_fma_f32 v[18:19], v[50:51], v[110:111], v[18:19]
	v_pk_fma_f32 v[18:19], v[52:53], v[112:113], v[18:19]
	v_pk_fma_f32 v[18:19], v[54:55], v[114:115], v[18:19]
	v_pk_fma_f32 v[18:19], v[56:57], v[216:217], v[18:19]
	v_pk_fma_f32 v[18:19], v[58:59], v[218:219], v[18:19]
	v_pk_fma_f32 v[18:19], v[60:61], v[220:221], v[18:19]
	v_pk_fma_f32 v[18:19], v[62:63], v[222:223], v[18:19]
	s_waitcnt vmcnt(19)
	v_cvt_pk_f32_fp8_e32 v[48:49], v166
	v_cvt_pk_f32_fp8_sdwa v[50:51], v166 src0_sel:WORD_1
	v_cvt_pk_f32_fp8_e32 v[52:53], v167
	v_cvt_pk_f32_fp8_sdwa v[54:55], v167 src0_sel:WORD_1
	v_cvt_pk_f32_fp8_e32 v[56:57], v168
	v_cvt_pk_f32_fp8_sdwa v[58:59], v168 src0_sel:WORD_1
	v_cvt_pk_f32_fp8_e32 v[60:61], v169
	v_cvt_pk_f32_fp8_sdwa v[62:63], v169 src0_sel:WORD_1
	global_load_dwordx4 v[166:169], v77, s[42:43] offset:640
	v_pk_fma_f32 v[20:21], v[48:49], v[108:109], v[20:21]
	v_pk_fma_f32 v[20:21], v[50:51], v[110:111], v[20:21]
	v_pk_fma_f32 v[20:21], v[52:53], v[112:113], v[20:21]
	v_pk_fma_f32 v[20:21], v[54:55], v[114:115], v[20:21]
	v_pk_fma_f32 v[20:21], v[56:57], v[216:217], v[20:21]
	v_pk_fma_f32 v[20:21], v[58:59], v[218:219], v[20:21]
	v_pk_fma_f32 v[20:21], v[60:61], v[220:221], v[20:21]
	v_pk_fma_f32 v[20:21], v[62:63], v[222:223], v[20:21]
	s_waitcnt vmcnt(19)
	v_cvt_pk_f32_fp8_e32 v[48:49], v170
	v_cvt_pk_f32_fp8_sdwa v[50:51], v170 src0_sel:WORD_1
	v_cvt_pk_f32_fp8_e32 v[52:53], v171
	v_cvt_pk_f32_fp8_sdwa v[54:55], v171 src0_sel:WORD_1
	v_cvt_pk_f32_fp8_e32 v[56:57], v172
	v_cvt_pk_f32_fp8_sdwa v[58:59], v172 src0_sel:WORD_1
	v_cvt_pk_f32_fp8_e32 v[60:61], v173
	v_cvt_pk_f32_fp8_sdwa v[62:63], v173 src0_sel:WORD_1
	global_load_dwordx4 v[170:173], v78, s[42:43] offset:640
	v_pk_fma_f32 v[22:23], v[48:49], v[108:109], v[22:23]
	v_pk_fma_f32 v[22:23], v[50:51], v[110:111], v[22:23]
	v_pk_fma_f32 v[22:23], v[52:53], v[112:113], v[22:23]
	v_pk_fma_f32 v[22:23], v[54:55], v[114:115], v[22:23]
	v_pk_fma_f32 v[22:23], v[56:57], v[216:217], v[22:23]
	v_pk_fma_f32 v[22:23], v[58:59], v[218:219], v[22:23]
	v_pk_fma_f32 v[22:23], v[60:61], v[220:221], v[22:23]
	v_pk_fma_f32 v[22:23], v[62:63], v[222:223], v[22:23]
	s_waitcnt vmcnt(19)
	v_cvt_pk_f32_fp8_e32 v[48:49], v180
	v_cvt_pk_f32_fp8_sdwa v[50:51], v180 src0_sel:WORD_1
	v_cvt_pk_f32_fp8_e32 v[52:53], v181
	v_cvt_pk_f32_fp8_sdwa v[54:55], v181 src0_sel:WORD_1
	v_cvt_pk_f32_fp8_e32 v[56:57], v182
	v_cvt_pk_f32_fp8_sdwa v[58:59], v182 src0_sel:WORD_1
	v_cvt_pk_f32_fp8_e32 v[60:61], v183
	v_cvt_pk_f32_fp8_sdwa v[62:63], v183 src0_sel:WORD_1
	global_load_dwordx4 v[180:183], v79, s[42:43] offset:640
	v_pk_fma_f32 v[24:25], v[48:49], v[108:109], v[24:25]
	v_pk_fma_f32 v[24:25], v[50:51], v[110:111], v[24:25]
	v_pk_fma_f32 v[24:25], v[52:53], v[112:113], v[24:25]
	v_pk_fma_f32 v[24:25], v[54:55], v[114:115], v[24:25]
	v_pk_fma_f32 v[24:25], v[56:57], v[216:217], v[24:25]
	v_pk_fma_f32 v[24:25], v[58:59], v[218:219], v[24:25]
	v_pk_fma_f32 v[24:25], v[60:61], v[220:221], v[24:25]
	v_pk_fma_f32 v[24:25], v[62:63], v[222:223], v[24:25]
	s_waitcnt vmcnt(19)
	v_cvt_pk_f32_fp8_e32 v[48:49], v184
	v_cvt_pk_f32_fp8_sdwa v[50:51], v184 src0_sel:WORD_1
	v_cvt_pk_f32_fp8_e32 v[52:53], v185
	v_cvt_pk_f32_fp8_sdwa v[54:55], v185 src0_sel:WORD_1
	v_cvt_pk_f32_fp8_e32 v[56:57], v186
	v_cvt_pk_f32_fp8_sdwa v[58:59], v186 src0_sel:WORD_1
	v_cvt_pk_f32_fp8_e32 v[60:61], v187
	v_cvt_pk_f32_fp8_sdwa v[62:63], v187 src0_sel:WORD_1
	global_load_dwordx4 v[184:187], v80, s[42:43] offset:640
	v_pk_fma_f32 v[26:27], v[48:49], v[108:109], v[26:27]
	v_pk_fma_f32 v[26:27], v[50:51], v[110:111], v[26:27]
	v_pk_fma_f32 v[26:27], v[52:53], v[112:113], v[26:27]
	v_pk_fma_f32 v[26:27], v[54:55], v[114:115], v[26:27]
	v_pk_fma_f32 v[26:27], v[56:57], v[216:217], v[26:27]
	v_pk_fma_f32 v[26:27], v[58:59], v[218:219], v[26:27]
	v_pk_fma_f32 v[26:27], v[60:61], v[220:221], v[26:27]
	v_pk_fma_f32 v[26:27], v[62:63], v[222:223], v[26:27]
	s_waitcnt vmcnt(19)
;     ...
;     for (int m = 0; m < 16; m += 2) {
;         const u32x4_t a0 = *(const u32x4_t*)(hp + m * 64), a1 = *(const u32x4_t*)(hp + m * 64 + 64);
; #pragma unroll
;         for (int t = 0; t < NTL; ++t) FP8MM(a0, b0[t], acc[t]);
;         if (m + 2 < 16) {
; #pragma unroll
;             for (int t = 0; t < NTL; ++t) b0[t] = *(const u32x4_t*)(up[t] + (m + 2) * 64);
;         }
; #pragma unroll
;         for (int t = 0; t < NTL; ++t) FP8MM(a1, b1[t], acc[t]);
;         if (m + 3 < 16) {
; #pragma unroll
;             for (int t = 0; t < NTL; ++t) b1[t] = *(const u32x4_t*)(up[t] + (m + 3) * 64);
;         }
;     }
	v_cvt_pk_f32_fp8_e32 v[48:49], v188
	v_cvt_pk_f32_fp8_sdwa v[50:51], v188 src0_sel:WORD_1
	v_cvt_pk_f32_fp8_e32 v[52:53], v189
	v_cvt_pk_f32_fp8_sdwa v[54:55], v189 src0_sel:WORD_1
	v_cvt_pk_f32_fp8_e32 v[56:57], v190
	v_cvt_pk_f32_fp8_sdwa v[58:59], v190 src0_sel:WORD_1
	v_cvt_pk_f32_fp8_e32 v[60:61], v191
	v_cvt_pk_f32_fp8_sdwa v[62:63], v191 src0_sel:WORD_1
	global_load_dwordx4 v[188:191], v81, s[42:43] offset:640
	v_pk_fma_f32 v[28:29], v[48:49], v[108:109], v[28:29]
	v_pk_fma_f32 v[28:29], v[50:51], v[110:111], v[28:29]
	v_pk_fma_f32 v[28:29], v[52:53], v[112:113], v[28:29]
	v_pk_fma_f32 v[28:29], v[54:55], v[114:115], v[28:29]
	v_pk_fma_f32 v[28:29], v[56:57], v[216:217], v[28:29]
	v_pk_fma_f32 v[28:29], v[58:59], v[218:219], v[28:29]
	v_pk_fma_f32 v[28:29], v[60:61], v[220:221], v[28:29]
	v_pk_fma_f32 v[28:29], v[62:63], v[222:223], v[28:29]
	s_waitcnt vmcnt(19)
	v_cvt_pk_f32_fp8_e32 v[48:49], v192
	v_cvt_pk_f32_fp8_sdwa v[50:51], v192 src0_sel:WORD_1
	v_cvt_pk_f32_fp8_e32 v[52:53], v193
	v_cvt_pk_f32_fp8_sdwa v[54:55], v193 src0_sel:WORD_1
	v_cvt_pk_f32_fp8_e32 v[56:57], v194
	v_cvt_pk_f32_fp8_sdwa v[58:59], v194 src0_sel:WORD_1
	v_cvt_pk_f32_fp8_e32 v[60:61], v195
	v_cvt_pk_f32_fp8_sdwa v[62:63], v195 src0_sel:WORD_1
	global_load_dwordx4 v[192:195], v82, s[42:43] offset:640
	v_pk_fma_f32 v[30:31], v[48:49], v[108:109], v[30:31]
	v_pk_fma_f32 v[30:31], v[50:51], v[110:111], v[30:31]
	v_pk_fma_f32 v[30:31], v[52:53], v[112:113], v[30:31]
	v_pk_fma_f32 v[30:31], v[54:55], v[114:115], v[30:31]
	v_pk_fma_f32 v[30:31], v[56:57], v[216:217], v[30:31]
	v_pk_fma_f32 v[30:31], v[58:59], v[218:219], v[30:31]
	v_pk_fma_f32 v[30:31], v[60:61], v[220:221], v[30:31]
	v_pk_fma_f32 v[30:31], v[62:63], v[222:223], v[30:31]
	s_waitcnt vmcnt(19)
	v_cvt_pk_f32_fp8_e32 v[48:49], v196
	v_cvt_pk_f32_fp8_sdwa v[50:51], v196 src0_sel:WORD_1
	v_cvt_pk_f32_fp8_e32 v[52:53], v197
	v_cvt_pk_f32_fp8_sdwa v[54:55], v197 src0_sel:WORD_1
	v_cvt_pk_f32_fp8_e32 v[56:57], v198
	v_cvt_pk_f32_fp8_sdwa v[58:59], v198 src0_sel:WORD_1
	v_cvt_pk_f32_fp8_e32 v[60:61], v199
	v_cvt_pk_f32_fp8_sdwa v[62:63], v199 src0_sel:WORD_1
	global_load_dwordx4 v[196:199], v83, s[42:43] offset:640
	v_pk_fma_f32 v[32:33], v[48:49], v[108:109], v[32:33]
	v_pk_fma_f32 v[32:33], v[50:51], v[110:111], v[32:33]
	v_pk_fma_f32 v[32:33], v[52:53], v[112:113], v[32:33]
	v_pk_fma_f32 v[32:33], v[54:55], v[114:115], v[32:33]
	v_pk_fma_f32 v[32:33], v[56:57], v[216:217], v[32:33]
	v_pk_fma_f32 v[32:33], v[58:59], v[218:219], v[32:33]
	v_pk_fma_f32 v[32:33], v[60:61], v[220:221], v[32:33]
	v_pk_fma_f32 v[32:33], v[62:63], v[222:223], v[32:33]
	s_waitcnt vmcnt(18)
	v_cvt_pk_f32_fp8_e32 v[108:109], v88
	v_cvt_pk_f32_fp8_sdwa v[110:111], v88 src0_sel:WORD_1
	v_cvt_pk_f32_fp8_e32 v[112:113], v89
	v_cvt_pk_f32_fp8_sdwa v[114:115], v89 src0_sel:WORD_1
	v_cvt_pk_f32_fp8_e32 v[216:217], v90
	v_cvt_pk_f32_fp8_sdwa v[218:219], v90 src0_sel:WORD_1
	v_cvt_pk_f32_fp8_e32 v[220:221], v91
	v_cvt_pk_f32_fp8_sdwa v[222:223], v91 src0_sel:WORD_1
	v_cvt_pk_f32_fp8_e32 v[48:49], v92
	v_cvt_pk_f32_fp8_sdwa v[50:51], v92 src0_sel:WORD_1
	v_cvt_pk_f32_fp8_e32 v[52:53], v93
	v_cvt_pk_f32_fp8_sdwa v[54:55], v93 src0_sel:WORD_1
	v_cvt_pk_f32_fp8_e32 v[56:57], v94
	v_cvt_pk_f32_fp8_sdwa v[58:59], v94 src0_sel:WORD_1
	v_cvt_pk_f32_fp8_e32 v[60:61], v95
	v_cvt_pk_f32_fp8_sdwa v[62:63], v95 src0_sel:WORD_1
	v_pk_fma_f32 v[108:109], v[48:49], v[44:45], v[108:109]
	v_pk_fma_f32 v[110:111], v[50:51], v[44:45], v[110:111]
	v_pk_fma_f32 v[112:113], v[52:53], v[44:45], v[112:113]
	v_pk_fma_f32 v[114:115], v[54:55], v[44:45], v[114:115]
	v_pk_fma_f32 v[216:217], v[56:57], v[44:45], v[216:217]
	v_pk_fma_f32 v[218:219], v[58:59], v[44:45], v[218:219]
	v_pk_fma_f32 v[220:221], v[60:61], v[44:45], v[220:221]
	v_pk_fma_f32 v[222:223], v[62:63], v[44:45], v[222:223]
	global_load_dwordx4 v[88:91], v4, s[44:45] offset:768
	global_load_dwordx4 v[92:95], v8, s[44:45] offset:768
	s_waitcnt vmcnt(19)
	v_cvt_pk_f32_fp8_e32 v[48:49], v130
	v_cvt_pk_f32_fp8_sdwa v[50:51], v130 src0_sel:WORD_1
	v_cvt_pk_f32_fp8_e32 v[52:53], v131
	v_cvt_pk_f32_fp8_sdwa v[54:55], v131 src0_sel:WORD_1
	v_cvt_pk_f32_fp8_e32 v[56:57], v132
	v_cvt_pk_f32_fp8_sdwa v[58:59], v132 src0_sel:WORD_1
	v_cvt_pk_f32_fp8_e32 v[60:61], v133
	v_cvt_pk_f32_fp8_sdwa v[62:63], v133 src0_sel:WORD_1
	global_load_dwordx4 v[130:133], v76, s[42:43] offset:768
	v_pk_fma_f32 v[18:19], v[48:49], v[108:109], v[18:19]
	v_pk_fma_f32 v[18:19], v[50:51], v[110:111], v[18:19]
	v_pk_fma_f32 v[18:19], v[52:53], v[112:113], v[18:19]
	v_pk_fma_f32 v[18:19], v[54:55], v[114:115], v[18:19]
	v_pk_fma_f32 v[18:19], v[56:57], v[216:217], v[18:19]
	v_pk_fma_f32 v[18:19], v[58:59], v[218:219], v[18:19]
	v_pk_fma_f32 v[18:19], v[60:61], v[220:221], v[18:19]
	v_pk_fma_f32 v[18:19], v[62:63], v[222:223], v[18:19]
	s_waitcnt vmcnt(19)
	v_cvt_pk_f32_fp8_e32 v[48:49], v134
	v_cvt_pk_f32_fp8_sdwa v[50:51], v134 src0_sel:WORD_1
	v_cvt_pk_f32_fp8_e32 v[52:53], v135
	v_cvt_pk_f32_fp8_sdwa v[54:55], v135 src0_sel:WORD_1
	v_cvt_pk_f32_fp8_e32 v[56:57], v136
	v_cvt_pk_f32_fp8_sdwa v[58:59], v136 src0_sel:WORD_1
	v_cvt_pk_f32_fp8_e32 v[60:61], v137
	v_cvt_pk_f32_fp8_sdwa v[62:63], v137 src0_sel:WORD_1
	global_load_dwordx4 v[134:137], v77, s[42:43] offset:768
	v_pk_fma_f32 v[20:21], v[48:49], v[108:109], v[20:21]
	v_pk_fma_f32 v[20:21], v[50:51], v[110:111], v[20:21]
	v_pk_fma_f32 v[20:21], v[52:53], v[112:113], v[20:21]
	v_pk_fma_f32 v[20:21], v[54:55], v[114:115], v[20:21]
	v_pk_fma_f32 v[20:21], v[56:57], v[216:217], v[20:21]
	v_pk_fma_f32 v[20:21], v[58:59], v[218:219], v[20:21]
	v_pk_fma_f32 v[20:21], v[60:61], v[220:221], v[20:21]
	v_pk_fma_f32 v[20:21], v[62:63], v[222:223], v[20:21]
	s_waitcnt vmcnt(19)
;     ...
;     for (int m = 0; m < 16; m += 2) {
;         const u32x4_t a0 = *(const u32x4_t*)(hp + m * 64), a1 = *(const u32x4_t*)(hp + m * 64 + 64);
; #pragma unroll
;         for (int t = 0; t < NTL; ++t) FP8MM(a0, b0[t], acc[t]);
;         if (m + 2 < 16) {
; #pragma unroll
;             for (int t = 0; t < NTL; ++t) b0[t] = *(const u32x4_t*)(up[t] + (m + 2) * 64);
;         }
; #pragma unroll
;         for (int t = 0; t < NTL; ++t) FP8MM(a1, b1[t], acc[t]);
;         if (m + 3 < 16) {
; #pragma unroll
;             for (int t = 0; t < NTL; ++t) b1[t] = *(const u32x4_t*)(up[t] + (m + 3) * 64);
;         }
;     }
	v_cvt_pk_f32_fp8_e32 v[48:49], v138
	v_cvt_pk_f32_fp8_sdwa v[50:51], v138 src0_sel:WORD_1
	v_cvt_pk_f32_fp8_e32 v[52:53], v139
	v_cvt_pk_f32_fp8_sdwa v[54:55], v139 src0_sel:WORD_1
	v_cvt_pk_f32_fp8_e32 v[56:57], v140
	v_cvt_pk_f32_fp8_sdwa v[58:59], v140 src0_sel:WORD_1
	v_cvt_pk_f32_fp8_e32 v[60:61], v141
	v_cvt_pk_f32_fp8_sdwa v[62:63], v141 src0_sel:WORD_1
	global_load_dwordx4 v[138:141], v78, s[42:43] offset:768
	v_pk_fma_f32 v[22:23], v[48:49], v[108:109], v[22:23]
	v_pk_fma_f32 v[22:23], v[50:51], v[110:111], v[22:23]
	v_pk_fma_f32 v[22:23], v[52:53], v[112:113], v[22:23]
	v_pk_fma_f32 v[22:23], v[54:55], v[114:115], v[22:23]
	v_pk_fma_f32 v[22:23], v[56:57], v[216:217], v[22:23]
	v_pk_fma_f32 v[22:23], v[58:59], v[218:219], v[22:23]
	v_pk_fma_f32 v[22:23], v[60:61], v[220:221], v[22:23]
	v_pk_fma_f32 v[22:23], v[62:63], v[222:223], v[22:23]
	s_waitcnt vmcnt(19)
	v_cvt_pk_f32_fp8_e32 v[48:49], v142
	v_cvt_pk_f32_fp8_sdwa v[50:51], v142 src0_sel:WORD_1
	v_cvt_pk_f32_fp8_e32 v[52:53], v143
	v_cvt_pk_f32_fp8_sdwa v[54:55], v143 src0_sel:WORD_1
	v_cvt_pk_f32_fp8_e32 v[56:57], v144
	v_cvt_pk_f32_fp8_sdwa v[58:59], v144 src0_sel:WORD_1
	v_cvt_pk_f32_fp8_e32 v[60:61], v145
	v_cvt_pk_f32_fp8_sdwa v[62:63], v145 src0_sel:WORD_1
	global_load_dwordx4 v[142:145], v79, s[42:43] offset:768
	v_pk_fma_f32 v[24:25], v[48:49], v[108:109], v[24:25]
	v_pk_fma_f32 v[24:25], v[50:51], v[110:111], v[24:25]
	v_pk_fma_f32 v[24:25], v[52:53], v[112:113], v[24:25]
	v_pk_fma_f32 v[24:25], v[54:55], v[114:115], v[24:25]
	v_pk_fma_f32 v[24:25], v[56:57], v[216:217], v[24:25]
	v_pk_fma_f32 v[24:25], v[58:59], v[218:219], v[24:25]
	v_pk_fma_f32 v[24:25], v[60:61], v[220:221], v[24:25]
	v_pk_fma_f32 v[24:25], v[62:63], v[222:223], v[24:25]
	s_waitcnt vmcnt(19)
	v_cvt_pk_f32_fp8_e32 v[48:49], v146
	v_cvt_pk_f32_fp8_sdwa v[50:51], v146 src0_sel:WORD_1
	v_cvt_pk_f32_fp8_e32 v[52:53], v147
	v_cvt_pk_f32_fp8_sdwa v[54:55], v147 src0_sel:WORD_1
	v_cvt_pk_f32_fp8_e32 v[56:57], v148
	v_cvt_pk_f32_fp8_sdwa v[58:59], v148 src0_sel:WORD_1
	v_cvt_pk_f32_fp8_e32 v[60:61], v149
	v_cvt_pk_f32_fp8_sdwa v[62:63], v149 src0_sel:WORD_1
	global_load_dwordx4 v[146:149], v80, s[42:43] offset:768
	v_pk_fma_f32 v[26:27], v[48:49], v[108:109], v[26:27]
	v_pk_fma_f32 v[26:27], v[50:51], v[110:111], v[26:27]
	v_pk_fma_f32 v[26:27], v[52:53], v[112:113], v[26:27]
	v_pk_fma_f32 v[26:27], v[54:55], v[114:115], v[26:27]
	v_pk_fma_f32 v[26:27], v[56:57], v[216:217], v[26:27]
	v_pk_fma_f32 v[26:27], v[58:59], v[218:219], v[26:27]
	v_pk_fma_f32 v[26:27], v[60:61], v[220:221], v[26:27]
	v_pk_fma_f32 v[26:27], v[62:63], v[222:223], v[26:27]
	s_waitcnt vmcnt(19)
	v_cvt_pk_f32_fp8_e32 v[48:49], v150
	v_cvt_pk_f32_fp8_sdwa v[50:51], v150 src0_sel:WORD_1
	v_cvt_pk_f32_fp8_e32 v[52:53], v151
	v_cvt_pk_f32_fp8_sdwa v[54:55], v151 src0_sel:WORD_1
	v_cvt_pk_f32_fp8_e32 v[56:57], v152
	v_cvt_pk_f32_fp8_sdwa v[58:59], v152 src0_sel:WORD_1
	v_cvt_pk_f32_fp8_e32 v[60:61], v153
	v_cvt_pk_f32_fp8_sdwa v[62:63], v153 src0_sel:WORD_1
	global_load_dwordx4 v[150:153], v81, s[42:43] offset:768
	v_pk_fma_f32 v[28:29], v[48:49], v[108:109], v[28:29]
	v_pk_fma_f32 v[28:29], v[50:51], v[110:111], v[28:29]
	v_pk_fma_f32 v[28:29], v[52:53], v[112:113], v[28:29]
	v_pk_fma_f32 v[28:29], v[54:55], v[114:115], v[28:29]
	v_pk_fma_f32 v[28:29], v[56:57], v[216:217], v[28:29]
	v_pk_fma_f32 v[28:29], v[58:59], v[218:219], v[28:29]
	v_pk_fma_f32 v[28:29], v[60:61], v[220:221], v[28:29]
	v_pk_fma_f32 v[28:29], v[62:63], v[222:223], v[28:29]
	s_waitcnt vmcnt(19)
	v_cvt_pk_f32_fp8_e32 v[48:49], v154
	v_cvt_pk_f32_fp8_sdwa v[50:51], v154 src0_sel:WORD_1
	v_cvt_pk_f32_fp8_e32 v[52:53], v155
	v_cvt_pk_f32_fp8_sdwa v[54:55], v155 src0_sel:WORD_1
	v_cvt_pk_f32_fp8_e32 v[56:57], v156
	v_cvt_pk_f32_fp8_sdwa v[58:59], v156 src0_sel:WORD_1
	v_cvt_pk_f32_fp8_e32 v[60:61], v157
	v_cvt_pk_f32_fp8_sdwa v[62:63], v157 src0_sel:WORD_1
	global_load_dwordx4 v[154:157], v82, s[42:43] offset:768
	v_pk_fma_f32 v[30:31], v[48:49], v[108:109], v[30:31]
	v_pk_fma_f32 v[30:31], v[50:51], v[110:111], v[30:31]
	v_pk_fma_f32 v[30:31], v[52:53], v[112:113], v[30:31]
	v_pk_fma_f32 v[30:31], v[54:55], v[114:115], v[30:31]
	v_pk_fma_f32 v[30:31], v[56:57], v[216:217], v[30:31]
	v_pk_fma_f32 v[30:31], v[58:59], v[218:219], v[30:31]
	v_pk_fma_f32 v[30:31], v[60:61], v[220:221], v[30:31]
	v_pk_fma_f32 v[30:31], v[62:63], v[222:223], v[30:31]
	s_waitcnt vmcnt(19)
	v_cvt_pk_f32_fp8_e32 v[48:49], v158
	v_cvt_pk_f32_fp8_sdwa v[50:51], v158 src0_sel:WORD_1
	v_cvt_pk_f32_fp8_e32 v[52:53], v159
	v_cvt_pk_f32_fp8_sdwa v[54:55], v159 src0_sel:WORD_1
	v_cvt_pk_f32_fp8_e32 v[56:57], v160
	v_cvt_pk_f32_fp8_sdwa v[58:59], v160 src0_sel:WORD_1
	v_cvt_pk_f32_fp8_e32 v[60:61], v161
	v_cvt_pk_f32_fp8_sdwa v[62:63], v161 src0_sel:WORD_1
	global_load_dwordx4 v[158:161], v83, s[42:43] offset:768
	v_pk_fma_f32 v[32:33], v[48:49], v[108:109], v[32:33]
	v_pk_fma_f32 v[32:33], v[50:51], v[110:111], v[32:33]
	v_pk_fma_f32 v[32:33], v[52:53], v[112:113], v[32:33]
	v_pk_fma_f32 v[32:33], v[54:55], v[114:115], v[32:33]
	v_pk_fma_f32 v[32:33], v[56:57], v[216:217], v[32:33]
	v_pk_fma_f32 v[32:33], v[58:59], v[218:219], v[32:33]
	v_pk_fma_f32 v[32:33], v[60:61], v[220:221], v[32:33]
	v_pk_fma_f32 v[32:33], v[62:63], v[222:223], v[32:33]
	s_waitcnt vmcnt(18)
;     ...
;     for (int m = 0; m < 16; m += 2) {
;         const u32x4_t a0 = *(const u32x4_t*)(hp + m * 64), a1 = *(const u32x4_t*)(hp + m * 64 + 64);
; #pragma unroll
;         for (int t = 0; t < NTL; ++t) FP8MM(a0, b0[t], acc[t]);
;         if (m + 2 < 16) {
; #pragma unroll
;             for (int t = 0; t < NTL; ++t) b0[t] = *(const u32x4_t*)(up[t] + (m + 2) * 64);
;         }
; #pragma unroll
;         for (int t = 0; t < NTL; ++t) FP8MM(a1, b1[t], acc[t]);
;         if (m + 3 < 16) {
; #pragma unroll
;             for (int t = 0; t < NTL; ++t) b1[t] = *(const u32x4_t*)(up[t] + (m + 3) * 64);
;         }
;     }
	v_cvt_pk_f32_fp8_e32 v[108:109], v96
	v_cvt_pk_f32_fp8_sdwa v[110:111], v96 src0_sel:WORD_1
	v_cvt_pk_f32_fp8_e32 v[112:113], v97
	v_cvt_pk_f32_fp8_sdwa v[114:115], v97 src0_sel:WORD_1
	v_cvt_pk_f32_fp8_e32 v[216:217], v98
	v_cvt_pk_f32_fp8_sdwa v[218:219], v98 src0_sel:WORD_1
	v_cvt_pk_f32_fp8_e32 v[220:221], v99
	v_cvt_pk_f32_fp8_sdwa v[222:223], v99 src0_sel:WORD_1
	v_cvt_pk_f32_fp8_e32 v[48:49], v104
	v_cvt_pk_f32_fp8_sdwa v[50:51], v104 src0_sel:WORD_1
	v_cvt_pk_f32_fp8_e32 v[52:53], v105
	v_cvt_pk_f32_fp8_sdwa v[54:55], v105 src0_sel:WORD_1
	v_cvt_pk_f32_fp8_e32 v[56:57], v106
	v_cvt_pk_f32_fp8_sdwa v[58:59], v106 src0_sel:WORD_1
	v_cvt_pk_f32_fp8_e32 v[60:61], v107
	v_cvt_pk_f32_fp8_sdwa v[62:63], v107 src0_sel:WORD_1
	v_pk_fma_f32 v[108:109], v[48:49], v[44:45], v[108:109]
	v_pk_fma_f32 v[110:111], v[50:51], v[44:45], v[110:111]
	v_pk_fma_f32 v[112:113], v[52:53], v[44:45], v[112:113]
	v_pk_fma_f32 v[114:115], v[54:55], v[44:45], v[114:115]
	v_pk_fma_f32 v[216:217], v[56:57], v[44:45], v[216:217]
	v_pk_fma_f32 v[218:219], v[58:59], v[44:45], v[218:219]
	v_pk_fma_f32 v[220:221], v[60:61], v[44:45], v[220:221]
	v_pk_fma_f32 v[222:223], v[62:63], v[44:45], v[222:223]
	global_load_dwordx4 v[96:99], v4, s[44:45] offset:896
	global_load_dwordx4 v[104:107], v8, s[44:45] offset:896
	s_waitcnt vmcnt(19)
	v_cvt_pk_f32_fp8_e32 v[48:49], v162
	v_cvt_pk_f32_fp8_sdwa v[50:51], v162 src0_sel:WORD_1
	v_cvt_pk_f32_fp8_e32 v[52:53], v163
	v_cvt_pk_f32_fp8_sdwa v[54:55], v163 src0_sel:WORD_1
	v_cvt_pk_f32_fp8_e32 v[56:57], v164
	v_cvt_pk_f32_fp8_sdwa v[58:59], v164 src0_sel:WORD_1
	v_cvt_pk_f32_fp8_e32 v[60:61], v165
	v_cvt_pk_f32_fp8_sdwa v[62:63], v165 src0_sel:WORD_1
	global_load_dwordx4 v[162:165], v76, s[42:43] offset:896
	v_pk_fma_f32 v[18:19], v[48:49], v[108:109], v[18:19]
	v_pk_fma_f32 v[18:19], v[50:51], v[110:111], v[18:19]
	v_pk_fma_f32 v[18:19], v[52:53], v[112:113], v[18:19]
	v_pk_fma_f32 v[18:19], v[54:55], v[114:115], v[18:19]
	v_pk_fma_f32 v[18:19], v[56:57], v[216:217], v[18:19]
	v_pk_fma_f32 v[18:19], v[58:59], v[218:219], v[18:19]
	v_pk_fma_f32 v[18:19], v[60:61], v[220:221], v[18:19]
	v_pk_fma_f32 v[18:19], v[62:63], v[222:223], v[18:19]
	s_waitcnt vmcnt(19)
	v_cvt_pk_f32_fp8_e32 v[48:49], v166
	v_cvt_pk_f32_fp8_sdwa v[50:51], v166 src0_sel:WORD_1
	v_cvt_pk_f32_fp8_e32 v[52:53], v167
	v_cvt_pk_f32_fp8_sdwa v[54:55], v167 src0_sel:WORD_1
	v_cvt_pk_f32_fp8_e32 v[56:57], v168
	v_cvt_pk_f32_fp8_sdwa v[58:59], v168 src0_sel:WORD_1
	v_cvt_pk_f32_fp8_e32 v[60:61], v169
	v_cvt_pk_f32_fp8_sdwa v[62:63], v169 src0_sel:WORD_1
	global_load_dwordx4 v[166:169], v77, s[42:43] offset:896
	v_pk_fma_f32 v[20:21], v[48:49], v[108:109], v[20:21]
	v_pk_fma_f32 v[20:21], v[50:51], v[110:111], v[20:21]
	v_pk_fma_f32 v[20:21], v[52:53], v[112:113], v[20:21]
	v_pk_fma_f32 v[20:21], v[54:55], v[114:115], v[20:21]
	v_pk_fma_f32 v[20:21], v[56:57], v[216:217], v[20:21]
	v_pk_fma_f32 v[20:21], v[58:59], v[218:219], v[20:21]
	v_pk_fma_f32 v[20:21], v[60:61], v[220:221], v[20:21]
	v_pk_fma_f32 v[20:21], v[62:63], v[222:223], v[20:21]
	s_waitcnt vmcnt(19)
	v_cvt_pk_f32_fp8_e32 v[48:49], v170
	v_cvt_pk_f32_fp8_sdwa v[50:51], v170 src0_sel:WORD_1
	v_cvt_pk_f32_fp8_e32 v[52:53], v171
	v_cvt_pk_f32_fp8_sdwa v[54:55], v171 src0_sel:WORD_1
	v_cvt_pk_f32_fp8_e32 v[56:57], v172
	v_cvt_pk_f32_fp8_sdwa v[58:59], v172 src0_sel:WORD_1
	v_cvt_pk_f32_fp8_e32 v[60:61], v173
	v_cvt_pk_f32_fp8_sdwa v[62:63], v173 src0_sel:WORD_1
	global_load_dwordx4 v[170:173], v78, s[42:43] offset:896
	v_pk_fma_f32 v[22:23], v[48:49], v[108:109], v[22:23]
	v_pk_fma_f32 v[22:23], v[50:51], v[110:111], v[22:23]
	v_pk_fma_f32 v[22:23], v[52:53], v[112:113], v[22:23]
	v_pk_fma_f32 v[22:23], v[54:55], v[114:115], v[22:23]
	v_pk_fma_f32 v[22:23], v[56:57], v[216:217], v[22:23]
	v_pk_fma_f32 v[22:23], v[58:59], v[218:219], v[22:23]
	v_pk_fma_f32 v[22:23], v[60:61], v[220:221], v[22:23]
	v_pk_fma_f32 v[22:23], v[62:63], v[222:223], v[22:23]
	s_waitcnt vmcnt(19)
	v_cvt_pk_f32_fp8_e32 v[48:49], v180
	v_cvt_pk_f32_fp8_sdwa v[50:51], v180 src0_sel:WORD_1
	v_cvt_pk_f32_fp8_e32 v[52:53], v181
	v_cvt_pk_f32_fp8_sdwa v[54:55], v181 src0_sel:WORD_1
	v_cvt_pk_f32_fp8_e32 v[56:57], v182
	v_cvt_pk_f32_fp8_sdwa v[58:59], v182 src0_sel:WORD_1
	v_cvt_pk_f32_fp8_e32 v[60:61], v183
	v_cvt_pk_f32_fp8_sdwa v[62:63], v183 src0_sel:WORD_1
	global_load_dwordx4 v[180:183], v79, s[42:43] offset:896
	v_pk_fma_f32 v[24:25], v[48:49], v[108:109], v[24:25]
	v_pk_fma_f32 v[24:25], v[50:51], v[110:111], v[24:25]
	v_pk_fma_f32 v[24:25], v[52:53], v[112:113], v[24:25]
	v_pk_fma_f32 v[24:25], v[54:55], v[114:115], v[24:25]
	v_pk_fma_f32 v[24:25], v[56:57], v[216:217], v[24:25]
	v_pk_fma_f32 v[24:25], v[58:59], v[218:219], v[24:25]
	v_pk_fma_f32 v[24:25], v[60:61], v[220:221], v[24:25]
	v_pk_fma_f32 v[24:25], v[62:63], v[222:223], v[24:25]
	s_waitcnt vmcnt(19)
	v_cvt_pk_f32_fp8_e32 v[48:49], v184
	v_cvt_pk_f32_fp8_sdwa v[50:51], v184 src0_sel:WORD_1
	v_cvt_pk_f32_fp8_e32 v[52:53], v185
	v_cvt_pk_f32_fp8_sdwa v[54:55], v185 src0_sel:WORD_1
	v_cvt_pk_f32_fp8_e32 v[56:57], v186
	v_cvt_pk_f32_fp8_sdwa v[58:59], v186 src0_sel:WORD_1
	v_cvt_pk_f32_fp8_e32 v[60:61], v187
	v_cvt_pk_f32_fp8_sdwa v[62:63], v187 src0_sel:WORD_1
	global_load_dwordx4 v[184:187], v80, s[42:43] offset:896
	v_pk_fma_f32 v[26:27], v[48:49], v[108:109], v[26:27]
	v_pk_fma_f32 v[26:27], v[50:51], v[110:111], v[26:27]
	v_pk_fma_f32 v[26:27], v[52:53], v[112:113], v[26:27]
	v_pk_fma_f32 v[26:27], v[54:55], v[114:115], v[26:27]
	v_pk_fma_f32 v[26:27], v[56:57], v[216:217], v[26:27]
	v_pk_fma_f32 v[26:27], v[58:59], v[218:219], v[26:27]
	v_pk_fma_f32 v[26:27], v[60:61], v[220:221], v[26:27]
	v_pk_fma_f32 v[26:27], v[62:63], v[222:223], v[26:27]
	s_waitcnt vmcnt(19)
;     ...
;     for (int m = 0; m < 16; m += 2) {
;         const u32x4_t a0 = *(const u32x4_t*)(hp + m * 64), a1 = *(const u32x4_t*)(hp + m * 64 + 64);
; #pragma unroll
;         for (int t = 0; t < NTL; ++t) FP8MM(a0, b0[t], acc[t]);
;         if (m + 2 < 16) {
; #pragma unroll
;             for (int t = 0; t < NTL; ++t) b0[t] = *(const u32x4_t*)(up[t] + (m + 2) * 64);
;         }
; #pragma unroll
;         for (int t = 0; t < NTL; ++t) FP8MM(a1, b1[t], acc[t]);
;         if (m + 3 < 16) {
; #pragma unroll
;             for (int t = 0; t < NTL; ++t) b1[t] = *(const u32x4_t*)(up[t] + (m + 3) * 64);
;         }
;     }
	v_cvt_pk_f32_fp8_e32 v[48:49], v188
	v_cvt_pk_f32_fp8_sdwa v[50:51], v188 src0_sel:WORD_1
	v_cvt_pk_f32_fp8_e32 v[52:53], v189
	v_cvt_pk_f32_fp8_sdwa v[54:55], v189 src0_sel:WORD_1
	v_cvt_pk_f32_fp8_e32 v[56:57], v190
	v_cvt_pk_f32_fp8_sdwa v[58:59], v190 src0_sel:WORD_1
	v_cvt_pk_f32_fp8_e32 v[60:61], v191
	v_cvt_pk_f32_fp8_sdwa v[62:63], v191 src0_sel:WORD_1
	global_load_dwordx4 v[188:191], v81, s[42:43] offset:896
	v_pk_fma_f32 v[28:29], v[48:49], v[108:109], v[28:29]
	v_pk_fma_f32 v[28:29], v[50:51], v[110:111], v[28:29]
	v_pk_fma_f32 v[28:29], v[52:53], v[112:113], v[28:29]
	v_pk_fma_f32 v[28:29], v[54:55], v[114:115], v[28:29]
	v_pk_fma_f32 v[28:29], v[56:57], v[216:217], v[28:29]
	v_pk_fma_f32 v[28:29], v[58:59], v[218:219], v[28:29]
	v_pk_fma_f32 v[28:29], v[60:61], v[220:221], v[28:29]
	v_pk_fma_f32 v[28:29], v[62:63], v[222:223], v[28:29]
	s_waitcnt vmcnt(19)
	v_cvt_pk_f32_fp8_e32 v[48:49], v192
	v_cvt_pk_f32_fp8_sdwa v[50:51], v192 src0_sel:WORD_1
	v_cvt_pk_f32_fp8_e32 v[52:53], v193
	v_cvt_pk_f32_fp8_sdwa v[54:55], v193 src0_sel:WORD_1
	v_cvt_pk_f32_fp8_e32 v[56:57], v194
	v_cvt_pk_f32_fp8_sdwa v[58:59], v194 src0_sel:WORD_1
	v_cvt_pk_f32_fp8_e32 v[60:61], v195
	v_cvt_pk_f32_fp8_sdwa v[62:63], v195 src0_sel:WORD_1
	global_load_dwordx4 v[192:195], v82, s[42:43] offset:896
	v_pk_fma_f32 v[30:31], v[48:49], v[108:109], v[30:31]
	v_pk_fma_f32 v[30:31], v[50:51], v[110:111], v[30:31]
	v_pk_fma_f32 v[30:31], v[52:53], v[112:113], v[30:31]
	v_pk_fma_f32 v[30:31], v[54:55], v[114:115], v[30:31]
	v_pk_fma_f32 v[30:31], v[56:57], v[216:217], v[30:31]
	v_pk_fma_f32 v[30:31], v[58:59], v[218:219], v[30:31]
	v_pk_fma_f32 v[30:31], v[60:61], v[220:221], v[30:31]
	v_pk_fma_f32 v[30:31], v[62:63], v[222:223], v[30:31]
	s_waitcnt vmcnt(19)
	v_cvt_pk_f32_fp8_e32 v[48:49], v196
	v_cvt_pk_f32_fp8_sdwa v[50:51], v196 src0_sel:WORD_1
	v_cvt_pk_f32_fp8_e32 v[52:53], v197
	v_cvt_pk_f32_fp8_sdwa v[54:55], v197 src0_sel:WORD_1
	v_cvt_pk_f32_fp8_e32 v[56:57], v198
	v_cvt_pk_f32_fp8_sdwa v[58:59], v198 src0_sel:WORD_1
	v_cvt_pk_f32_fp8_e32 v[60:61], v199
	v_cvt_pk_f32_fp8_sdwa v[62:63], v199 src0_sel:WORD_1
	global_load_dwordx4 v[196:199], v83, s[42:43] offset:896
	v_pk_fma_f32 v[32:33], v[48:49], v[108:109], v[32:33]
	v_pk_fma_f32 v[32:33], v[50:51], v[110:111], v[32:33]
	v_pk_fma_f32 v[32:33], v[52:53], v[112:113], v[32:33]
	v_pk_fma_f32 v[32:33], v[54:55], v[114:115], v[32:33]
	v_pk_fma_f32 v[32:33], v[56:57], v[216:217], v[32:33]
	v_pk_fma_f32 v[32:33], v[58:59], v[218:219], v[32:33]
	v_pk_fma_f32 v[32:33], v[60:61], v[220:221], v[32:33]
	v_pk_fma_f32 v[32:33], v[62:63], v[222:223], v[32:33]
	s_waitcnt vmcnt(18)
	v_cvt_pk_f32_fp8_e32 v[108:109], v88
	v_cvt_pk_f32_fp8_sdwa v[110:111], v88 src0_sel:WORD_1
	v_cvt_pk_f32_fp8_e32 v[112:113], v89
	v_cvt_pk_f32_fp8_sdwa v[114:115], v89 src0_sel:WORD_1
	v_cvt_pk_f32_fp8_e32 v[216:217], v90
	v_cvt_pk_f32_fp8_sdwa v[218:219], v90 src0_sel:WORD_1
	v_cvt_pk_f32_fp8_e32 v[220:221], v91
	v_cvt_pk_f32_fp8_sdwa v[222:223], v91 src0_sel:WORD_1
	v_cvt_pk_f32_fp8_e32 v[48:49], v92
	v_cvt_pk_f32_fp8_sdwa v[50:51], v92 src0_sel:WORD_1
	v_cvt_pk_f32_fp8_e32 v[52:53], v93
	v_cvt_pk_f32_fp8_sdwa v[54:55], v93 src0_sel:WORD_1
	v_cvt_pk_f32_fp8_e32 v[56:57], v94
	v_cvt_pk_f32_fp8_sdwa v[58:59], v94 src0_sel:WORD_1
	v_cvt_pk_f32_fp8_e32 v[60:61], v95
	v_cvt_pk_f32_fp8_sdwa v[62:63], v95 src0_sel:WORD_1
	v_pk_fma_f32 v[108:109], v[48:49], v[44:45], v[108:109]
	v_pk_fma_f32 v[110:111], v[50:51], v[44:45], v[110:111]
	v_pk_fma_f32 v[112:113], v[52:53], v[44:45], v[112:113]
	v_pk_fma_f32 v[114:115], v[54:55], v[44:45], v[114:115]
	v_pk_fma_f32 v[216:217], v[56:57], v[44:45], v[216:217]
	v_pk_fma_f32 v[218:219], v[58:59], v[44:45], v[218:219]
	v_pk_fma_f32 v[220:221], v[60:61], v[44:45], v[220:221]
	v_pk_fma_f32 v[222:223], v[62:63], v[44:45], v[222:223]
	s_waitcnt vmcnt(17)
	v_cvt_pk_f32_fp8_e32 v[48:49], v130
	v_cvt_pk_f32_fp8_sdwa v[50:51], v130 src0_sel:WORD_1
	v_cvt_pk_f32_fp8_e32 v[52:53], v131
	v_cvt_pk_f32_fp8_sdwa v[54:55], v131 src0_sel:WORD_1
	v_cvt_pk_f32_fp8_e32 v[56:57], v132
	v_cvt_pk_f32_fp8_sdwa v[58:59], v132 src0_sel:WORD_1
	v_cvt_pk_f32_fp8_e32 v[60:61], v133
	v_cvt_pk_f32_fp8_sdwa v[62:63], v133 src0_sel:WORD_1
	v_pk_fma_f32 v[18:19], v[48:49], v[108:109], v[18:19]
	v_pk_fma_f32 v[18:19], v[50:51], v[110:111], v[18:19]
	v_pk_fma_f32 v[18:19], v[52:53], v[112:113], v[18:19]
	v_pk_fma_f32 v[18:19], v[54:55], v[114:115], v[18:19]
	v_pk_fma_f32 v[18:19], v[56:57], v[216:217], v[18:19]
	v_pk_fma_f32 v[18:19], v[58:59], v[218:219], v[18:19]
	v_pk_fma_f32 v[18:19], v[60:61], v[220:221], v[18:19]
	v_pk_fma_f32 v[18:19], v[62:63], v[222:223], v[18:19]
	s_waitcnt vmcnt(16)
	v_cvt_pk_f32_fp8_e32 v[48:49], v134
	v_cvt_pk_f32_fp8_sdwa v[50:51], v134 src0_sel:WORD_1
	v_cvt_pk_f32_fp8_e32 v[52:53], v135
	v_cvt_pk_f32_fp8_sdwa v[54:55], v135 src0_sel:WORD_1
	v_cvt_pk_f32_fp8_e32 v[56:57], v136
	v_cvt_pk_f32_fp8_sdwa v[58:59], v136 src0_sel:WORD_1
	v_cvt_pk_f32_fp8_e32 v[60:61], v137
	v_cvt_pk_f32_fp8_sdwa v[62:63], v137 src0_sel:WORD_1
	v_pk_fma_f32 v[20:21], v[48:49], v[108:109], v[20:21]
	v_pk_fma_f32 v[20:21], v[50:51], v[110:111], v[20:21]
	v_pk_fma_f32 v[20:21], v[52:53], v[112:113], v[20:21]
	v_pk_fma_f32 v[20:21], v[54:55], v[114:115], v[20:21]
	v_pk_fma_f32 v[20:21], v[56:57], v[216:217], v[20:21]
	v_pk_fma_f32 v[20:21], v[58:59], v[218:219], v[20:21]
	v_pk_fma_f32 v[20:21], v[60:61], v[220:221], v[20:21]
	v_pk_fma_f32 v[20:21], v[62:63], v[222:223], v[20:21]
	s_waitcnt vmcnt(15)
;     ...
;     for (int m = 0; m < 16; m += 2) {
;         const u32x4_t a0 = *(const u32x4_t*)(hp + m * 64), a1 = *(const u32x4_t*)(hp + m * 64 + 64);
; #pragma unroll
;         for (int t = 0; t < NTL; ++t) FP8MM(a0, b0[t], acc[t]);
;         if (m + 2 < 16) {
; #pragma unroll
;             for (int t = 0; t < NTL; ++t) b0[t] = *(const u32x4_t*)(up[t] + (m + 2) * 64);
;         }
; #pragma unroll
;         for (int t = 0; t < NTL; ++t) FP8MM(a1, b1[t], acc[t]);
;         if (m + 3 < 16) {
; #pragma unroll
;             for (int t = 0; t < NTL; ++t) b1[t] = *(const u32x4_t*)(up[t] + (m + 3) * 64);
;         }
;     }
	v_cvt_pk_f32_fp8_e32 v[48:49], v138
	v_cvt_pk_f32_fp8_sdwa v[50:51], v138 src0_sel:WORD_1
	v_cvt_pk_f32_fp8_e32 v[52:53], v139
	v_cvt_pk_f32_fp8_sdwa v[54:55], v139 src0_sel:WORD_1
	v_cvt_pk_f32_fp8_e32 v[56:57], v140
	v_cvt_pk_f32_fp8_sdwa v[58:59], v140 src0_sel:WORD_1
	v_cvt_pk_f32_fp8_e32 v[60:61], v141
	v_cvt_pk_f32_fp8_sdwa v[62:63], v141 src0_sel:WORD_1
	v_pk_fma_f32 v[22:23], v[48:49], v[108:109], v[22:23]
	v_pk_fma_f32 v[22:23], v[50:51], v[110:111], v[22:23]
	v_pk_fma_f32 v[22:23], v[52:53], v[112:113], v[22:23]
	v_pk_fma_f32 v[22:23], v[54:55], v[114:115], v[22:23]
	v_pk_fma_f32 v[22:23], v[56:57], v[216:217], v[22:23]
	v_pk_fma_f32 v[22:23], v[58:59], v[218:219], v[22:23]
	v_pk_fma_f32 v[22:23], v[60:61], v[220:221], v[22:23]
	v_pk_fma_f32 v[22:23], v[62:63], v[222:223], v[22:23]
	s_waitcnt vmcnt(14)
	v_cvt_pk_f32_fp8_e32 v[48:49], v142
	v_cvt_pk_f32_fp8_sdwa v[50:51], v142 src0_sel:WORD_1
	v_cvt_pk_f32_fp8_e32 v[52:53], v143
	v_cvt_pk_f32_fp8_sdwa v[54:55], v143 src0_sel:WORD_1
	v_cvt_pk_f32_fp8_e32 v[56:57], v144
	v_cvt_pk_f32_fp8_sdwa v[58:59], v144 src0_sel:WORD_1
	v_cvt_pk_f32_fp8_e32 v[60:61], v145
	v_cvt_pk_f32_fp8_sdwa v[62:63], v145 src0_sel:WORD_1
	v_pk_fma_f32 v[24:25], v[48:49], v[108:109], v[24:25]
	v_pk_fma_f32 v[24:25], v[50:51], v[110:111], v[24:25]
	v_pk_fma_f32 v[24:25], v[52:53], v[112:113], v[24:25]
	v_pk_fma_f32 v[24:25], v[54:55], v[114:115], v[24:25]
	v_pk_fma_f32 v[24:25], v[56:57], v[216:217], v[24:25]
	v_pk_fma_f32 v[24:25], v[58:59], v[218:219], v[24:25]
	v_pk_fma_f32 v[24:25], v[60:61], v[220:221], v[24:25]
	v_pk_fma_f32 v[24:25], v[62:63], v[222:223], v[24:25]
	s_waitcnt vmcnt(13)
	v_cvt_pk_f32_fp8_e32 v[48:49], v146
	v_cvt_pk_f32_fp8_sdwa v[50:51], v146 src0_sel:WORD_1
	v_cvt_pk_f32_fp8_e32 v[52:53], v147
	v_cvt_pk_f32_fp8_sdwa v[54:55], v147 src0_sel:WORD_1
	v_cvt_pk_f32_fp8_e32 v[56:57], v148
	v_cvt_pk_f32_fp8_sdwa v[58:59], v148 src0_sel:WORD_1
	v_cvt_pk_f32_fp8_e32 v[60:61], v149
	v_cvt_pk_f32_fp8_sdwa v[62:63], v149 src0_sel:WORD_1
	v_pk_fma_f32 v[26:27], v[48:49], v[108:109], v[26:27]
	v_pk_fma_f32 v[26:27], v[50:51], v[110:111], v[26:27]
	v_pk_fma_f32 v[26:27], v[52:53], v[112:113], v[26:27]
	v_pk_fma_f32 v[26:27], v[54:55], v[114:115], v[26:27]
	v_pk_fma_f32 v[26:27], v[56:57], v[216:217], v[26:27]
	v_pk_fma_f32 v[26:27], v[58:59], v[218:219], v[26:27]
	v_pk_fma_f32 v[26:27], v[60:61], v[220:221], v[26:27]
	v_pk_fma_f32 v[26:27], v[62:63], v[222:223], v[26:27]
	s_waitcnt vmcnt(12)
	v_cvt_pk_f32_fp8_e32 v[48:49], v150
	v_cvt_pk_f32_fp8_sdwa v[50:51], v150 src0_sel:WORD_1
	v_cvt_pk_f32_fp8_e32 v[52:53], v151
	v_cvt_pk_f32_fp8_sdwa v[54:55], v151 src0_sel:WORD_1
	v_cvt_pk_f32_fp8_e32 v[56:57], v152
	v_cvt_pk_f32_fp8_sdwa v[58:59], v152 src0_sel:WORD_1
	v_cvt_pk_f32_fp8_e32 v[60:61], v153
	v_cvt_pk_f32_fp8_sdwa v[62:63], v153 src0_sel:WORD_1
	v_pk_fma_f32 v[28:29], v[48:49], v[108:109], v[28:29]
	v_pk_fma_f32 v[28:29], v[50:51], v[110:111], v[28:29]
	v_pk_fma_f32 v[28:29], v[52:53], v[112:113], v[28:29]
	v_pk_fma_f32 v[28:29], v[54:55], v[114:115], v[28:29]
	v_pk_fma_f32 v[28:29], v[56:57], v[216:217], v[28:29]
	v_pk_fma_f32 v[28:29], v[58:59], v[218:219], v[28:29]
	v_pk_fma_f32 v[28:29], v[60:61], v[220:221], v[28:29]
	v_pk_fma_f32 v[28:29], v[62:63], v[222:223], v[28:29]
	s_waitcnt vmcnt(11)
	v_cvt_pk_f32_fp8_e32 v[48:49], v154
	v_cvt_pk_f32_fp8_sdwa v[50:51], v154 src0_sel:WORD_1
	v_cvt_pk_f32_fp8_e32 v[52:53], v155
	v_cvt_pk_f32_fp8_sdwa v[54:55], v155 src0_sel:WORD_1
	v_cvt_pk_f32_fp8_e32 v[56:57], v156
	v_cvt_pk_f32_fp8_sdwa v[58:59], v156 src0_sel:WORD_1
	v_cvt_pk_f32_fp8_e32 v[60:61], v157
	v_cvt_pk_f32_fp8_sdwa v[62:63], v157 src0_sel:WORD_1
	v_pk_fma_f32 v[30:31], v[48:49], v[108:109], v[30:31]
	v_pk_fma_f32 v[30:31], v[50:51], v[110:111], v[30:31]
	v_pk_fma_f32 v[30:31], v[52:53], v[112:113], v[30:31]
	v_pk_fma_f32 v[30:31], v[54:55], v[114:115], v[30:31]
	v_pk_fma_f32 v[30:31], v[56:57], v[216:217], v[30:31]
	v_pk_fma_f32 v[30:31], v[58:59], v[218:219], v[30:31]
	v_pk_fma_f32 v[30:31], v[60:61], v[220:221], v[30:31]
	v_pk_fma_f32 v[30:31], v[62:63], v[222:223], v[30:31]
	s_waitcnt vmcnt(10)
	v_cvt_pk_f32_fp8_e32 v[48:49], v158
	v_cvt_pk_f32_fp8_sdwa v[50:51], v158 src0_sel:WORD_1
	v_cvt_pk_f32_fp8_e32 v[52:53], v159
	v_cvt_pk_f32_fp8_sdwa v[54:55], v159 src0_sel:WORD_1
	v_cvt_pk_f32_fp8_e32 v[56:57], v160
	v_cvt_pk_f32_fp8_sdwa v[58:59], v160 src0_sel:WORD_1
	v_cvt_pk_f32_fp8_e32 v[60:61], v161
	v_cvt_pk_f32_fp8_sdwa v[62:63], v161 src0_sel:WORD_1
	v_pk_fma_f32 v[32:33], v[48:49], v[108:109], v[32:33]
	v_pk_fma_f32 v[32:33], v[50:51], v[110:111], v[32:33]
	v_pk_fma_f32 v[32:33], v[52:53], v[112:113], v[32:33]
	v_pk_fma_f32 v[32:33], v[54:55], v[114:115], v[32:33]
	v_pk_fma_f32 v[32:33], v[56:57], v[216:217], v[32:33]
	v_pk_fma_f32 v[32:33], v[58:59], v[218:219], v[32:33]
	v_pk_fma_f32 v[32:33], v[60:61], v[220:221], v[32:33]
	v_pk_fma_f32 v[32:33], v[62:63], v[222:223], v[32:33]
	s_waitcnt vmcnt(8)
	v_cvt_pk_f32_fp8_e32 v[108:109], v96
	v_cvt_pk_f32_fp8_sdwa v[110:111], v96 src0_sel:WORD_1
	v_cvt_pk_f32_fp8_e32 v[112:113], v97
	v_cvt_pk_f32_fp8_sdwa v[114:115], v97 src0_sel:WORD_1
	v_cvt_pk_f32_fp8_e32 v[216:217], v98
	v_cvt_pk_f32_fp8_sdwa v[218:219], v98 src0_sel:WORD_1
	v_cvt_pk_f32_fp8_e32 v[220:221], v99
	v_cvt_pk_f32_fp8_sdwa v[222:223], v99 src0_sel:WORD_1
	v_cvt_pk_f32_fp8_e32 v[48:49], v104
	v_cvt_pk_f32_fp8_sdwa v[50:51], v104 src0_sel:WORD_1
	v_cvt_pk_f32_fp8_e32 v[52:53], v105
	v_cvt_pk_f32_fp8_sdwa v[54:55], v105 src0_sel:WORD_1
	v_cvt_pk_f32_fp8_e32 v[56:57], v106
	v_cvt_pk_f32_fp8_sdwa v[58:59], v106 src0_sel:WORD_1
	v_cvt_pk_f32_fp8_e32 v[60:61], v107
	v_cvt_pk_f32_fp8_sdwa v[62:63], v107 src0_sel:WORD_1
	v_pk_fma_f32 v[108:109], v[48:49], v[44:45], v[108:109]
	v_pk_fma_f32 v[110:111], v[50:51], v[44:45], v[110:111]
	v_pk_fma_f32 v[112:113], v[52:53], v[44:45], v[112:113]
	v_pk_fma_f32 v[114:115], v[54:55], v[44:45], v[114:115]
	v_pk_fma_f32 v[216:217], v[56:57], v[44:45], v[216:217]
	v_pk_fma_f32 v[218:219], v[58:59], v[44:45], v[218:219]
	v_pk_fma_f32 v[220:221], v[60:61], v[44:45], v[220:221]
	v_pk_fma_f32 v[222:223], v[62:63], v[44:45], v[222:223]
	s_waitcnt vmcnt(7)
;     ...
;     for (int m = 0; m < 16; m += 2) {
;         const u32x4_t a0 = *(const u32x4_t*)(hp + m * 64), a1 = *(const u32x4_t*)(hp + m * 64 + 64);
; #pragma unroll
;         for (int t = 0; t < NTL; ++t) FP8MM(a0, b0[t], acc[t]);
;         if (m + 2 < 16) {
; #pragma unroll
;             for (int t = 0; t < NTL; ++t) b0[t] = *(const u32x4_t*)(up[t] + (m + 2) * 64);
;         }
; #pragma unroll
;         for (int t = 0; t < NTL; ++t) FP8MM(a1, b1[t], acc[t]);
;         if (m + 3 < 16) {
; #pragma unroll
;             for (int t = 0; t < NTL; ++t) b1[t] = *(const u32x4_t*)(up[t] + (m + 3) * 64);
;         }
;     }
	v_cvt_pk_f32_fp8_e32 v[48:49], v162
	v_cvt_pk_f32_fp8_sdwa v[50:51], v162 src0_sel:WORD_1
	v_cvt_pk_f32_fp8_e32 v[52:53], v163
	v_cvt_pk_f32_fp8_sdwa v[54:55], v163 src0_sel:WORD_1
	v_cvt_pk_f32_fp8_e32 v[56:57], v164
	v_cvt_pk_f32_fp8_sdwa v[58:59], v164 src0_sel:WORD_1
	v_cvt_pk_f32_fp8_e32 v[60:61], v165
	v_cvt_pk_f32_fp8_sdwa v[62:63], v165 src0_sel:WORD_1
	v_pk_fma_f32 v[18:19], v[48:49], v[108:109], v[18:19]
	v_pk_fma_f32 v[18:19], v[50:51], v[110:111], v[18:19]
	v_pk_fma_f32 v[18:19], v[52:53], v[112:113], v[18:19]
	v_pk_fma_f32 v[18:19], v[54:55], v[114:115], v[18:19]
	v_pk_fma_f32 v[18:19], v[56:57], v[216:217], v[18:19]
	v_pk_fma_f32 v[18:19], v[58:59], v[218:219], v[18:19]
	v_pk_fma_f32 v[18:19], v[60:61], v[220:221], v[18:19]
	v_pk_fma_f32 v[18:19], v[62:63], v[222:223], v[18:19]
	s_waitcnt vmcnt(6)
	v_cvt_pk_f32_fp8_e32 v[48:49], v166
	v_cvt_pk_f32_fp8_sdwa v[50:51], v166 src0_sel:WORD_1
	v_cvt_pk_f32_fp8_e32 v[52:53], v167
	v_cvt_pk_f32_fp8_sdwa v[54:55], v167 src0_sel:WORD_1
	v_cvt_pk_f32_fp8_e32 v[56:57], v168
	v_cvt_pk_f32_fp8_sdwa v[58:59], v168 src0_sel:WORD_1
	v_cvt_pk_f32_fp8_e32 v[60:61], v169
	v_cvt_pk_f32_fp8_sdwa v[62:63], v169 src0_sel:WORD_1
	v_pk_fma_f32 v[20:21], v[48:49], v[108:109], v[20:21]
	v_pk_fma_f32 v[20:21], v[50:51], v[110:111], v[20:21]
	v_pk_fma_f32 v[20:21], v[52:53], v[112:113], v[20:21]
	v_pk_fma_f32 v[20:21], v[54:55], v[114:115], v[20:21]
	v_pk_fma_f32 v[20:21], v[56:57], v[216:217], v[20:21]
	v_pk_fma_f32 v[20:21], v[58:59], v[218:219], v[20:21]
	v_pk_fma_f32 v[20:21], v[60:61], v[220:221], v[20:21]
	v_pk_fma_f32 v[20:21], v[62:63], v[222:223], v[20:21]
	s_waitcnt vmcnt(5)
	v_cvt_pk_f32_fp8_e32 v[48:49], v170
	v_cvt_pk_f32_fp8_sdwa v[50:51], v170 src0_sel:WORD_1
	v_cvt_pk_f32_fp8_e32 v[52:53], v171
	v_cvt_pk_f32_fp8_sdwa v[54:55], v171 src0_sel:WORD_1
	v_cvt_pk_f32_fp8_e32 v[56:57], v172
	v_cvt_pk_f32_fp8_sdwa v[58:59], v172 src0_sel:WORD_1
	v_cvt_pk_f32_fp8_e32 v[60:61], v173
	v_cvt_pk_f32_fp8_sdwa v[62:63], v173 src0_sel:WORD_1
	v_pk_fma_f32 v[22:23], v[48:49], v[108:109], v[22:23]
	v_pk_fma_f32 v[22:23], v[50:51], v[110:111], v[22:23]
	v_pk_fma_f32 v[22:23], v[52:53], v[112:113], v[22:23]
	v_pk_fma_f32 v[22:23], v[54:55], v[114:115], v[22:23]
	v_pk_fma_f32 v[22:23], v[56:57], v[216:217], v[22:23]
	v_pk_fma_f32 v[22:23], v[58:59], v[218:219], v[22:23]
	v_pk_fma_f32 v[22:23], v[60:61], v[220:221], v[22:23]
	v_pk_fma_f32 v[22:23], v[62:63], v[222:223], v[22:23]
	s_waitcnt vmcnt(4)
	v_cvt_pk_f32_fp8_e32 v[48:49], v180
	v_cvt_pk_f32_fp8_sdwa v[50:51], v180 src0_sel:WORD_1
	v_cvt_pk_f32_fp8_e32 v[52:53], v181
	v_cvt_pk_f32_fp8_sdwa v[54:55], v181 src0_sel:WORD_1
	v_cvt_pk_f32_fp8_e32 v[56:57], v182
	v_cvt_pk_f32_fp8_sdwa v[58:59], v182 src0_sel:WORD_1
	v_cvt_pk_f32_fp8_e32 v[60:61], v183
	v_cvt_pk_f32_fp8_sdwa v[62:63], v183 src0_sel:WORD_1
	v_pk_fma_f32 v[24:25], v[48:49], v[108:109], v[24:25]
	v_pk_fma_f32 v[24:25], v[50:51], v[110:111], v[24:25]
	v_pk_fma_f32 v[24:25], v[52:53], v[112:113], v[24:25]
	v_pk_fma_f32 v[24:25], v[54:55], v[114:115], v[24:25]
	v_pk_fma_f32 v[24:25], v[56:57], v[216:217], v[24:25]
	v_pk_fma_f32 v[24:25], v[58:59], v[218:219], v[24:25]
	v_pk_fma_f32 v[24:25], v[60:61], v[220:221], v[24:25]
	v_pk_fma_f32 v[24:25], v[62:63], v[222:223], v[24:25]
	s_waitcnt vmcnt(3)
	v_cvt_pk_f32_fp8_e32 v[48:49], v184
	v_cvt_pk_f32_fp8_sdwa v[50:51], v184 src0_sel:WORD_1
	v_cvt_pk_f32_fp8_e32 v[52:53], v185
	v_cvt_pk_f32_fp8_sdwa v[54:55], v185 src0_sel:WORD_1
	v_cvt_pk_f32_fp8_e32 v[56:57], v186
	v_cvt_pk_f32_fp8_sdwa v[58:59], v186 src0_sel:WORD_1
	v_cvt_pk_f32_fp8_e32 v[60:61], v187
	v_cvt_pk_f32_fp8_sdwa v[62:63], v187 src0_sel:WORD_1
	v_pk_fma_f32 v[26:27], v[48:49], v[108:109], v[26:27]
	v_pk_fma_f32 v[26:27], v[50:51], v[110:111], v[26:27]
	v_pk_fma_f32 v[26:27], v[52:53], v[112:113], v[26:27]
	v_pk_fma_f32 v[26:27], v[54:55], v[114:115], v[26:27]
	v_pk_fma_f32 v[26:27], v[56:57], v[216:217], v[26:27]
	v_pk_fma_f32 v[26:27], v[58:59], v[218:219], v[26:27]
	v_pk_fma_f32 v[26:27], v[60:61], v[220:221], v[26:27]
	v_pk_fma_f32 v[26:27], v[62:63], v[222:223], v[26:27]
	s_waitcnt vmcnt(2)
	v_cvt_pk_f32_fp8_e32 v[48:49], v188
	v_cvt_pk_f32_fp8_sdwa v[50:51], v188 src0_sel:WORD_1
	v_cvt_pk_f32_fp8_e32 v[52:53], v189
	v_cvt_pk_f32_fp8_sdwa v[54:55], v189 src0_sel:WORD_1
	v_cvt_pk_f32_fp8_e32 v[56:57], v190
	v_cvt_pk_f32_fp8_sdwa v[58:59], v190 src0_sel:WORD_1
	v_cvt_pk_f32_fp8_e32 v[60:61], v191
	v_cvt_pk_f32_fp8_sdwa v[62:63], v191 src0_sel:WORD_1
	v_pk_fma_f32 v[28:29], v[48:49], v[108:109], v[28:29]
	v_pk_fma_f32 v[28:29], v[50:51], v[110:111], v[28:29]
	v_pk_fma_f32 v[28:29], v[52:53], v[112:113], v[28:29]
	v_pk_fma_f32 v[28:29], v[54:55], v[114:115], v[28:29]
	v_pk_fma_f32 v[28:29], v[56:57], v[216:217], v[28:29]
	v_pk_fma_f32 v[28:29], v[58:59], v[218:219], v[28:29]
	v_pk_fma_f32 v[28:29], v[60:61], v[220:221], v[28:29]
	v_pk_fma_f32 v[28:29], v[62:63], v[222:223], v[28:29]
	s_waitcnt vmcnt(1)
; DEVI float gelu_f(float x) { const float u = 0.7978845608028654f * (x + 0.044715f * x * x * x); return x * __builtin_amdgcn_rcpf(1.f + __expf(-2.f * u)); }
;     ...
;     for (int t = 0; t < NTL; ++t) { const float lo = __shfl_xor(acc[t][0], 32); const float dot = (acc[t][0] + lo * (1.f / 32.f)) * s_u[t];
;         if (kq == 0) pl[t * 16 + n16] = (u32x2_t){(unsigned)e[t], __float_as_uint(g[t] * gelu_f(dot) * s_v[t])}; }
	v_cvt_pk_f32_fp8_e32 v[48:49], v192
	v_cvt_pk_f32_fp8_sdwa v[50:51], v192 src0_sel:WORD_1
	v_cvt_pk_f32_fp8_e32 v[52:53], v193
	v_cvt_pk_f32_fp8_sdwa v[54:55], v193 src0_sel:WORD_1
	v_cvt_pk_f32_fp8_e32 v[56:57], v194
	v_cvt_pk_f32_fp8_sdwa v[58:59], v194 src0_sel:WORD_1
	v_cvt_pk_f32_fp8_e32 v[60:61], v195
	v_cvt_pk_f32_fp8_sdwa v[62:63], v195 src0_sel:WORD_1
	v_pk_fma_f32 v[30:31], v[48:49], v[108:109], v[30:31]
	v_pk_fma_f32 v[30:31], v[50:51], v[110:111], v[30:31]
	v_pk_fma_f32 v[30:31], v[52:53], v[112:113], v[30:31]
	v_pk_fma_f32 v[30:31], v[54:55], v[114:115], v[30:31]
	v_pk_fma_f32 v[30:31], v[56:57], v[216:217], v[30:31]
	v_pk_fma_f32 v[30:31], v[58:59], v[218:219], v[30:31]
	v_pk_fma_f32 v[30:31], v[60:61], v[220:221], v[30:31]
	v_pk_fma_f32 v[30:31], v[62:63], v[222:223], v[30:31]
	s_waitcnt vmcnt(0)
	v_cvt_pk_f32_fp8_e32 v[48:49], v196
	v_cvt_pk_f32_fp8_sdwa v[50:51], v196 src0_sel:WORD_1
	v_cvt_pk_f32_fp8_e32 v[52:53], v197
	v_cvt_pk_f32_fp8_sdwa v[54:55], v197 src0_sel:WORD_1
	v_cvt_pk_f32_fp8_e32 v[56:57], v198
	v_cvt_pk_f32_fp8_sdwa v[58:59], v198 src0_sel:WORD_1
	v_cvt_pk_f32_fp8_e32 v[60:61], v199
	v_cvt_pk_f32_fp8_sdwa v[62:63], v199 src0_sel:WORD_1
	v_pk_fma_f32 v[32:33], v[48:49], v[108:109], v[32:33]
	v_pk_fma_f32 v[32:33], v[50:51], v[110:111], v[32:33]
	v_pk_fma_f32 v[32:33], v[52:53], v[112:113], v[32:33]
	v_pk_fma_f32 v[32:33], v[54:55], v[114:115], v[32:33]
	v_pk_fma_f32 v[32:33], v[56:57], v[216:217], v[32:33]
	v_pk_fma_f32 v[32:33], v[58:59], v[218:219], v[32:33]
	v_pk_fma_f32 v[32:33], v[60:61], v[220:221], v[32:33]
	v_pk_fma_f32 v[32:33], v[62:63], v[222:223], v[32:33]
	v_add_f32_e32 v34, v18, v19
	v_add_f32_e32 v35, v20, v21
	v_add_f32_e32 v36, v22, v23
	v_add_f32_e32 v37, v24, v25
	v_add_f32_e32 v38, v26, v27
	v_add_f32_e32 v39, v28, v29
	v_add_f32_e32 v40, v30, v31
	v_add_f32_e32 v41, v32, v33
	s_nop 1
	v_add_f32_dpp v34, v34, v34 quad_perm:[1,0,3,2] row_mask:0xf bank_mask:0xf
	v_add_f32_dpp v35, v35, v35 quad_perm:[1,0,3,2] row_mask:0xf bank_mask:0xf
	v_add_f32_dpp v36, v36, v36 quad_perm:[1,0,3,2] row_mask:0xf bank_mask:0xf
	v_add_f32_dpp v37, v37, v37 quad_perm:[1,0,3,2] row_mask:0xf bank_mask:0xf
	v_add_f32_dpp v38, v38, v38 quad_perm:[1,0,3,2] row_mask:0xf bank_mask:0xf
	v_add_f32_dpp v39, v39, v39 quad_perm:[1,0,3,2] row_mask:0xf bank_mask:0xf
	v_add_f32_dpp v40, v40, v40 quad_perm:[1,0,3,2] row_mask:0xf bank_mask:0xf
	v_add_f32_dpp v41, v41, v41 quad_perm:[1,0,3,2] row_mask:0xf bank_mask:0xf
	v_add_f32_dpp v34, v34, v34 quad_perm:[2,3,0,1] row_mask:0xf bank_mask:0xf
	v_add_f32_dpp v35, v35, v35 quad_perm:[2,3,0,1] row_mask:0xf bank_mask:0xf
	v_add_f32_dpp v36, v36, v36 quad_perm:[2,3,0,1] row_mask:0xf bank_mask:0xf
	v_add_f32_dpp v37, v37, v37 quad_perm:[2,3,0,1] row_mask:0xf bank_mask:0xf
	v_add_f32_dpp v38, v38, v38 quad_perm:[2,3,0,1] row_mask:0xf bank_mask:0xf
	v_add_f32_dpp v39, v39, v39 quad_perm:[2,3,0,1] row_mask:0xf bank_mask:0xf
	v_add_f32_dpp v40, v40, v40 quad_perm:[2,3,0,1] row_mask:0xf bank_mask:0xf
	v_add_f32_dpp v41, v41, v41 quad_perm:[2,3,0,1] row_mask:0xf bank_mask:0xf
	v_add_f32_dpp v34, v34, v34 row_half_mirror row_mask:0xf bank_mask:0xf
	v_add_f32_dpp v35, v35, v35 row_half_mirror row_mask:0xf bank_mask:0xf
	v_add_f32_dpp v36, v36, v36 row_half_mirror row_mask:0xf bank_mask:0xf
	v_add_f32_dpp v37, v37, v37 row_half_mirror row_mask:0xf bank_mask:0xf
	v_add_f32_dpp v38, v38, v38 row_half_mirror row_mask:0xf bank_mask:0xf
	v_add_f32_dpp v39, v39, v39 row_half_mirror row_mask:0xf bank_mask:0xf
	v_add_f32_dpp v40, v40, v40 row_half_mirror row_mask:0xf bank_mask:0xf
	v_add_f32_dpp v41, v41, v41 row_half_mirror row_mask:0xf bank_mask:0xf
	v_mov_b32_e32 v43, v34
	v_cmp_eq_u32_e32 vcc, 1, v2
	s_nop 1
	v_cndmask_b32_e32 v43, v43, v35, vcc
	v_cmp_eq_u32_e32 vcc, 2, v2
	s_nop 1
	v_cndmask_b32_e32 v43, v43, v36, vcc
	v_cmp_eq_u32_e32 vcc, 3, v2
	s_nop 1
	v_cndmask_b32_e32 v43, v43, v37, vcc
	v_cmp_eq_u32_e32 vcc, 4, v2
	s_nop 1
	v_cndmask_b32_e32 v43, v43, v38, vcc
	v_cmp_eq_u32_e32 vcc, 5, v2
	s_nop 1
	v_cndmask_b32_e32 v43, v43, v39, vcc
	v_cmp_eq_u32_e32 vcc, 6, v2
	s_nop 1
	v_cndmask_b32_e32 v43, v43, v40, vcc
	v_cmp_eq_u32_e32 vcc, 7, v2
	s_nop 1
	v_cndmask_b32_e32 v43, v43, v41, vcc
	s_waitcnt vmcnt(60)
	v_mul_f32_e32 v43, v43, v86
	v_mul_f32_e32 v46, 0x3d372713, v43
	v_mul_f32_e32 v46, v43, v46
	v_fma_f32 v46, v43, v46, v43
	v_mul_f32_e32 v46, 0x3f4c422a, v46
	v_mul_f32_e32 v46, -2.0, v46
	v_mul_f32_e32 v46, 0x3fb8aa3b, v46
	v_exp_f32_e32 v46, v46
	s_nop 0
	v_add_f32_e32 v46, 1.0, v46
	v_rcp_f32_e32 v46, v46
	s_nop 0
	v_mul_f32_e32 v43, v43, v46
	v_mul_f32_e32 v43, v85, v43
	v_mul_f32_e32 v85, v87, v43
	v_lshl_add_u32 v47, v210, 3, s85
	ds_write_b64 v47, v[84:85]
	s_branch .Lsu_done
.Lsu_done:
	v_mov_b32_e32 v4, 0
	s_mov_b32 s26, -16
	s_mov_b32 s27, s85
	v_mov_b32_e32 v5, v4
	s_waitcnt vmcnt(0)
	v_mov_b32_e32 v6, v4
	v_mov_b32_e32 v7, v4
	v_mov_b32_e32 v8, v4
	v_mov_b32_e32 v9, v4
	v_mov_b32_e32 v10, v4
	v_mov_b32_e32 v11, v4
	v_mov_b32_e32 v12, v4
	v_mov_b32_e32 v13, v4
	v_mov_b32_e32 v14, v4
	v_mov_b32_e32 v15, v4
	v_mov_b32_e32 v16, v4
	v_mov_b32_e32 v17, v4
	v_mov_b32_e32 v2, v4
	s_waitcnt lgkmcnt(0)
	v_mov_b32_e32 v3, v4
